# DN chunk path trimmed: dead loop-counter initialisation, no-op lgkmcnt waits and fall-through branches removed
# baseline (speedup 1.0000x reference)
.LBB0_853:
	ds_read_b128 v[22:25], v100
	ds_read_b128 v[18:21], v100 offset:16
	ds_read_b128 v[2:5], v100 offset:256
	ds_read_b128 v[6:9], v100 offset:272
	ds_read_b128 v[10:13], v100 offset:512
	ds_read_b128 v[14:17], v100 offset:528
	ds_read_b128 v[34:37], v100 offset:768
	ds_read_b128 v[38:41], v100 offset:784
	ds_read_b128 v[26:29], v100 offset:1024
	ds_read_b128 v[30:33], v100 offset:1040
	ds_read_b32 v94, v101 offset:1280
	ds_read_b64 v[96:97], v1 offset:1536
	s_lshl_b32 s6, s4, 4
	s_cmp_gt_u32 s4, 15
	s_cselect_b64 s[18:19], -1, 0
	s_mov_b64 s[48:49], -1
	s_and_b64 vcc, exec, s[18:19]
	s_cbranch_vccz .LBB0_855
	v_readlane_b32 s8, v254, 0
	s_sub_i32 s2, 0x8ff, s6
	s_add_i32 s3, s6, 0xffffff00
	v_readlane_b32 s9, v254, 1
	s_and_b64 s[10:11], s[8:9], exec
	s_cselect_b32 s2, s3, s2
	v_readlane_b32 s3, v254, 2
	s_add_i32 s46, s2, s3
	s_mov_b64 s[48:49], 0

.LBB0_863:
	s_waitcnt lgkmcnt(0)
	s_barrier
	ds_read_b128 v[22:25], v100 offset:25088
	ds_read_b128 v[18:21], v100 offset:25104
	ds_read_b128 v[2:5], v100 offset:25344
	ds_read_b128 v[6:9], v100 offset:25360
	ds_read_b128 v[10:13], v100 offset:25600
	ds_read_b128 v[14:17], v100 offset:25616
	ds_read_b128 v[34:37], v100 offset:25856
	ds_read_b128 v[38:41], v100 offset:25872
	ds_read_b128 v[26:29], v100 offset:26112
	ds_read_b128 v[30:33], v100 offset:26128
	ds_read_b32 v94, v101 offset:26368
	ds_read_b64 v[96:97], v1 offset:26624
	s_or_b32 s7, s6, 16
	s_mov_b64 s[46:47], -1
	s_and_b64 vcc, exec, s[18:19]
	s_cbranch_vccz .LBB0_865
	v_readlane_b32 s8, v254, 0
	s_sub_i32 s2, 0x8ff, s7
	s_addk_i32 s6, 0xff10
	v_readlane_b32 s9, v254, 1
	s_and_b64 s[10:11], s[8:9], exec
	s_cselect_b32 s2, s6, s2
	v_readlane_b32 s3, v254, 2
	s_add_i32 s18, s2, s3
	s_mov_b64 s[46:47], 0

.LBB0_900:
	ds_read_b128 v[30:33], v94
	ds_read_b128 v[26:29], v94 offset:16
	ds_read_b128 v[22:25], v94 offset:32
	ds_read_b128 v[18:21], v94 offset:48
	ds_read_b128 v[2:5], v94 offset:256
	ds_read_b128 v[6:9], v94 offset:272
	ds_read_b32 v73, v95 offset:512
	ds_read_b128 v[34:37], v1 offset:768
	ds_read_b128 v[14:17], v94 offset:288
	ds_read_b128 v[10:13], v94 offset:304
	s_lshl_b32 s6, s4, 4
	s_cmp_gt_u32 s4, 15
	s_cselect_b64 s[16:17], -1, 0
	s_mov_b64 s[46:47], -1
	s_and_b64 vcc, exec, s[16:17]
	s_cbranch_vccz .LBB0_902
	v_readlane_b32 s8, v254, 7
	s_sub_i32 s2, 0x8ff, s6
	s_add_i32 s3, s6, 0xffffff00
	v_readlane_b32 s9, v254, 8
	s_and_b64 s[10:11], s[8:9], exec
	s_cselect_b32 s2, s3, s2
	v_readlane_b32 s3, v254, 10
	s_add_i32 s18, s2, s3
	s_mov_b64 s[46:47], 0

.LBB0_906:
	s_nop 0
	v_readfirstlane_b32 s100, v92
	v_readfirstlane_b32 s101, v93
	s_sub_u32 s100, s100, m0
	s_subb_u32 s101, s101, 0
	s_waitcnt lgkmcnt(0)
	v_pk_mul_f32 v[114:115], v[34:35], v[74:75] op_sel_hi:[0,1]
	v_pk_mul_f32 v[116:117], v[34:35], v[78:79] op_sel_hi:[0,1]
	v_pk_fma_f32 v[106:107], v[114:115], v[2:3], 0 op_sel_hi:[1,1,0]
	v_pk_fma_f32 v[108:109], v[114:115], v[30:31], 0 op_sel_hi:[1,1,0]
	v_pk_mul_f32 v[118:119], v[34:35], v[80:81] op_sel_hi:[0,1]
	ds_read_b128 v[66:69], v94 offset:800
	v_pk_fma_f32 v[106:107], v[116:117], v[4:5], v[106:107]
	v_pk_fma_f32 v[108:109], v[116:117], v[32:33], v[108:109]
	v_pk_mul_f32 v[120:121], v[34:35], v[82:83] op_sel_hi:[0,1]
	ds_read_b128 v[62:65], v94 offset:816
	v_pk_fma_f32 v[106:107], v[118:119], v[6:7], v[106:107]
	v_pk_fma_f32 v[108:109], v[118:119], v[26:27], v[108:109]
	v_pk_mul_f32 v[122:123], v[34:35], v[84:85] op_sel_hi:[0,1]
	ds_read_b128 v[58:61], v94 offset:832
	v_pk_fma_f32 v[106:107], v[120:121], v[8:9], v[106:107]
	v_pk_fma_f32 v[108:109], v[120:121], v[28:29], v[108:109]
	v_pk_mul_f32 v[124:125], v[34:35], v[86:87] op_sel_hi:[0,1]
	ds_read_b128 v[54:57], v94 offset:848
	v_pk_fma_f32 v[106:107], v[122:123], v[14:15], v[106:107]
	v_pk_fma_f32 v[108:109], v[122:123], v[22:23], v[108:109]
	v_pk_mul_f32 v[126:127], v[34:35], v[88:89] op_sel_hi:[0,1]
	ds_read_b128 v[50:53], v94 offset:1056
	v_pk_fma_f32 v[106:107], v[124:125], v[16:17], v[106:107]
	v_pk_fma_f32 v[108:109], v[124:125], v[24:25], v[108:109]
	v_pk_mul_f32 v[128:129], v[34:35], v[90:91] op_sel_hi:[0,1]
	ds_read_b128 v[46:49], v94 offset:1072
	v_pk_fma_f32 v[106:107], v[126:127], v[10:11], v[106:107]
	v_pk_fma_f32 v[108:109], v[126:127], v[18:19], v[108:109]
	ds_read_b128 v[42:45], v94 offset:1088
	v_pk_fma_f32 v[106:107], v[128:129], v[12:13], v[106:107]
	v_pk_fma_f32 v[108:109], v[128:129], v[20:21], v[108:109]
	ds_read_b128 v[38:41], v94 offset:1104
	v_add_f32_e32 v130, v106, v107
	v_add_f32_e32 v131, v108, v109
	ds_read_b32 v0, v95 offset:1312
	v_add_f32_dpp v130, v130, v130 quad_perm:[1,0,3,2] row_mask:0xf bank_mask:0xf bound_ctrl:1
	v_add_f32_dpp v131, v131, v131 quad_perm:[1,0,3,2] row_mask:0xf bank_mask:0xf bound_ctrl:1
	ds_read_b96 v[70:72], v1 offset:1568
	v_add_f32_dpp v130, v130, v130 quad_perm:[2,3,0,1] row_mask:0xf bank_mask:0xf bound_ctrl:1
	v_add_f32_dpp v131, v131, v131 quad_perm:[2,3,0,1] row_mask:0xf bank_mask:0xf bound_ctrl:1
	v_sub_f32_e32 v130, v73, v130
	v_mul_f32_e32 v130, v35, v130
	v_fma_f32 v131, v36, v130, v131
	v_cvt_pk_bf16_f32 v132, v131, v131
	v_pk_fma_f32 v[74:75], v[2:3], v[130:131], v[114:115] op_sel_hi:[1,0,1]
	v_pk_fma_f32 v[78:79], v[4:5], v[130:131], v[116:117] op_sel_hi:[1,0,1]
	global_store_short v144, v132, s[100:101]
	v_pk_fma_f32 v[80:81], v[6:7], v[130:131], v[118:119] op_sel_hi:[1,0,1]
	v_pk_fma_f32 v[82:83], v[8:9], v[130:131], v[120:121] op_sel_hi:[1,0,1]
	v_pk_fma_f32 v[84:85], v[14:15], v[130:131], v[122:123] op_sel_hi:[1,0,1]
	v_pk_fma_f32 v[86:87], v[16:17], v[130:131], v[124:125] op_sel_hi:[1,0,1]
	v_pk_fma_f32 v[88:89], v[10:11], v[130:131], v[126:127] op_sel_hi:[1,0,1]
	v_pk_fma_f32 v[90:91], v[12:13], v[130:131], v[128:129] op_sel_hi:[1,0,1]
	s_waitcnt lgkmcnt(0)
	v_pk_mul_f32 v[114:115], v[70:71], v[74:75] op_sel_hi:[0,1]
	v_pk_mul_f32 v[116:117], v[70:71], v[78:79] op_sel_hi:[0,1]
	v_pk_fma_f32 v[110:111], v[114:115], v[50:51], 0 op_sel_hi:[1,1,0]
	v_pk_fma_f32 v[112:113], v[114:115], v[66:67], 0 op_sel_hi:[1,1,0]
	v_pk_mul_f32 v[118:119], v[70:71], v[80:81] op_sel_hi:[0,1]
	ds_read_b128 v[30:33], v94 offset:1600
	v_pk_fma_f32 v[110:111], v[116:117], v[52:53], v[110:111]
	v_pk_fma_f32 v[112:113], v[116:117], v[68:69], v[112:113]
	v_pk_mul_f32 v[120:121], v[70:71], v[82:83] op_sel_hi:[0,1]
	ds_read_b128 v[26:29], v94 offset:1616
	v_pk_fma_f32 v[110:111], v[118:119], v[46:47], v[110:111]
	v_pk_fma_f32 v[112:113], v[118:119], v[62:63], v[112:113]
	v_pk_mul_f32 v[122:123], v[70:71], v[84:85] op_sel_hi:[0,1]
	ds_read_b128 v[22:25], v94 offset:1632
	v_pk_fma_f32 v[110:111], v[120:121], v[48:49], v[110:111]
	v_pk_fma_f32 v[112:113], v[120:121], v[64:65], v[112:113]
	v_pk_mul_f32 v[124:125], v[70:71], v[86:87] op_sel_hi:[0,1]
	ds_read_b128 v[18:21], v94 offset:1648
	v_pk_fma_f32 v[110:111], v[122:123], v[42:43], v[110:111]
	v_pk_fma_f32 v[112:113], v[122:123], v[58:59], v[112:113]
	v_pk_mul_f32 v[126:127], v[70:71], v[88:89] op_sel_hi:[0,1]
	ds_read_b128 v[2:5], v94 offset:1856
	v_pk_fma_f32 v[110:111], v[124:125], v[44:45], v[110:111]
	v_pk_fma_f32 v[112:113], v[124:125], v[60:61], v[112:113]
	v_pk_mul_f32 v[128:129], v[70:71], v[90:91] op_sel_hi:[0,1]
	ds_read_b128 v[6:9], v94 offset:1872
	v_pk_fma_f32 v[110:111], v[126:127], v[38:39], v[110:111]
	v_pk_fma_f32 v[112:113], v[126:127], v[54:55], v[112:113]
	ds_read_b128 v[14:17], v94 offset:1888
	v_pk_fma_f32 v[110:111], v[128:129], v[40:41], v[110:111]
	v_pk_fma_f32 v[112:113], v[128:129], v[56:57], v[112:113]
	ds_read_b128 v[10:13], v94 offset:1904
	v_add_f32_e32 v134, v110, v111
	v_add_f32_e32 v135, v112, v113
	ds_read_b32 v73, v95 offset:2112
	v_add_f32_dpp v134, v134, v134 quad_perm:[1,0,3,2] row_mask:0xf bank_mask:0xf bound_ctrl:1
	v_add_f32_dpp v135, v135, v135 quad_perm:[1,0,3,2] row_mask:0xf bank_mask:0xf bound_ctrl:1
	ds_read_b96 v[34:36], v1 offset:2368
	v_add_f32_dpp v134, v134, v134 quad_perm:[2,3,0,1] row_mask:0xf bank_mask:0xf bound_ctrl:1
	v_add_f32_dpp v135, v135, v135 quad_perm:[2,3,0,1] row_mask:0xf bank_mask:0xf bound_ctrl:1
	v_sub_f32_e32 v134, v0, v134
	v_mul_f32_e32 v134, v71, v134
	v_fma_f32 v135, v72, v134, v135
	v_cvt_pk_bf16_f32 v133, v135, v135
	v_pk_fma_f32 v[74:75], v[50:51], v[134:135], v[114:115] op_sel_hi:[1,0,1]
	v_pk_fma_f32 v[78:79], v[52:53], v[134:135], v[116:117] op_sel_hi:[1,0,1]
	global_store_short v145, v133, s[100:101]
	v_pk_fma_f32 v[80:81], v[46:47], v[134:135], v[118:119] op_sel_hi:[1,0,1]
	v_pk_fma_f32 v[82:83], v[48:49], v[134:135], v[120:121] op_sel_hi:[1,0,1]
	v_pk_fma_f32 v[84:85], v[42:43], v[134:135], v[122:123] op_sel_hi:[1,0,1]
	v_pk_fma_f32 v[86:87], v[44:45], v[134:135], v[124:125] op_sel_hi:[1,0,1]
	v_pk_fma_f32 v[88:89], v[38:39], v[134:135], v[126:127] op_sel_hi:[1,0,1]
	v_pk_fma_f32 v[90:91], v[40:41], v[134:135], v[128:129] op_sel_hi:[1,0,1]
	s_waitcnt lgkmcnt(0)
	v_pk_mul_f32 v[114:115], v[34:35], v[74:75] op_sel_hi:[0,1]
	v_pk_mul_f32 v[116:117], v[34:35], v[78:79] op_sel_hi:[0,1]
	v_pk_fma_f32 v[106:107], v[114:115], v[2:3], 0 op_sel_hi:[1,1,0]
	v_pk_fma_f32 v[108:109], v[114:115], v[30:31], 0 op_sel_hi:[1,1,0]
	v_pk_mul_f32 v[118:119], v[34:35], v[80:81] op_sel_hi:[0,1]
	ds_read_b128 v[66:69], v94 offset:2400
	v_pk_fma_f32 v[106:107], v[116:117], v[4:5], v[106:107]
	v_pk_fma_f32 v[108:109], v[116:117], v[32:33], v[108:109]
	v_pk_mul_f32 v[120:121], v[34:35], v[82:83] op_sel_hi:[0,1]
	ds_read_b128 v[62:65], v94 offset:2416
	v_pk_fma_f32 v[106:107], v[118:119], v[6:7], v[106:107]
	v_pk_fma_f32 v[108:109], v[118:119], v[26:27], v[108:109]
	v_pk_mul_f32 v[122:123], v[34:35], v[84:85] op_sel_hi:[0,1]
	ds_read_b128 v[58:61], v94 offset:2432
	v_pk_fma_f32 v[106:107], v[120:121], v[8:9], v[106:107]
	v_pk_fma_f32 v[108:109], v[120:121], v[28:29], v[108:109]
	v_pk_mul_f32 v[124:125], v[34:35], v[86:87] op_sel_hi:[0,1]
	ds_read_b128 v[54:57], v94 offset:2448
	v_pk_fma_f32 v[106:107], v[122:123], v[14:15], v[106:107]
	v_pk_fma_f32 v[108:109], v[122:123], v[22:23], v[108:109]
	v_pk_mul_f32 v[126:127], v[34:35], v[88:89] op_sel_hi:[0,1]
	ds_read_b128 v[50:53], v94 offset:2656
	v_pk_fma_f32 v[106:107], v[124:125], v[16:17], v[106:107]
	v_pk_fma_f32 v[108:109], v[124:125], v[24:25], v[108:109]
	v_pk_mul_f32 v[128:129], v[34:35], v[90:91] op_sel_hi:[0,1]
	ds_read_b128 v[46:49], v94 offset:2672
	v_pk_fma_f32 v[106:107], v[126:127], v[10:11], v[106:107]
	v_pk_fma_f32 v[108:109], v[126:127], v[18:19], v[108:109]
	ds_read_b128 v[42:45], v94 offset:2688
	v_pk_fma_f32 v[106:107], v[128:129], v[12:13], v[106:107]
	v_pk_fma_f32 v[108:109], v[128:129], v[20:21], v[108:109]
	ds_read_b128 v[38:41], v94 offset:2704
	v_add_f32_e32 v130, v106, v107
	v_add_f32_e32 v131, v108, v109
	ds_read_b32 v0, v95 offset:2912
	v_add_f32_dpp v130, v130, v130 quad_perm:[1,0,3,2] row_mask:0xf bank_mask:0xf bound_ctrl:1
	v_add_f32_dpp v131, v131, v131 quad_perm:[1,0,3,2] row_mask:0xf bank_mask:0xf bound_ctrl:1
	ds_read_b96 v[70:72], v1 offset:3168
	v_add_f32_dpp v130, v130, v130 quad_perm:[2,3,0,1] row_mask:0xf bank_mask:0xf bound_ctrl:1
	v_add_f32_dpp v131, v131, v131 quad_perm:[2,3,0,1] row_mask:0xf bank_mask:0xf bound_ctrl:1
	v_sub_f32_e32 v130, v73, v130
	v_mul_f32_e32 v130, v35, v130
	v_fma_f32 v131, v36, v130, v131
	v_cvt_pk_bf16_f32 v132, v131, v131
	v_pk_fma_f32 v[74:75], v[2:3], v[130:131], v[114:115] op_sel_hi:[1,0,1]
	v_pk_fma_f32 v[78:79], v[4:5], v[130:131], v[116:117] op_sel_hi:[1,0,1]
	global_store_short v146, v132, s[100:101]
	v_pk_fma_f32 v[80:81], v[6:7], v[130:131], v[118:119] op_sel_hi:[1,0,1]
	v_pk_fma_f32 v[82:83], v[8:9], v[130:131], v[120:121] op_sel_hi:[1,0,1]
	v_pk_fma_f32 v[84:85], v[14:15], v[130:131], v[122:123] op_sel_hi:[1,0,1]
	v_pk_fma_f32 v[86:87], v[16:17], v[130:131], v[124:125] op_sel_hi:[1,0,1]
	v_pk_fma_f32 v[88:89], v[10:11], v[130:131], v[126:127] op_sel_hi:[1,0,1]
	v_pk_fma_f32 v[90:91], v[12:13], v[130:131], v[128:129] op_sel_hi:[1,0,1]
	s_waitcnt lgkmcnt(0)
	v_pk_mul_f32 v[114:115], v[70:71], v[74:75] op_sel_hi:[0,1]
	v_pk_mul_f32 v[116:117], v[70:71], v[78:79] op_sel_hi:[0,1]
	v_pk_fma_f32 v[110:111], v[114:115], v[50:51], 0 op_sel_hi:[1,1,0]
	v_pk_fma_f32 v[112:113], v[114:115], v[66:67], 0 op_sel_hi:[1,1,0]
	v_pk_mul_f32 v[118:119], v[70:71], v[80:81] op_sel_hi:[0,1]
	ds_read_b128 v[30:33], v94 offset:3200
	v_pk_fma_f32 v[110:111], v[116:117], v[52:53], v[110:111]
	v_pk_fma_f32 v[112:113], v[116:117], v[68:69], v[112:113]
	v_pk_mul_f32 v[120:121], v[70:71], v[82:83] op_sel_hi:[0,1]
	ds_read_b128 v[26:29], v94 offset:3216
	v_pk_fma_f32 v[110:111], v[118:119], v[46:47], v[110:111]
	v_pk_fma_f32 v[112:113], v[118:119], v[62:63], v[112:113]
	v_pk_mul_f32 v[122:123], v[70:71], v[84:85] op_sel_hi:[0,1]
	ds_read_b128 v[22:25], v94 offset:3232
	v_pk_fma_f32 v[110:111], v[120:121], v[48:49], v[110:111]
	v_pk_fma_f32 v[112:113], v[120:121], v[64:65], v[112:113]
	v_pk_mul_f32 v[124:125], v[70:71], v[86:87] op_sel_hi:[0,1]
	ds_read_b128 v[18:21], v94 offset:3248
	v_pk_fma_f32 v[110:111], v[122:123], v[42:43], v[110:111]
	v_pk_fma_f32 v[112:113], v[122:123], v[58:59], v[112:113]
	v_pk_mul_f32 v[126:127], v[70:71], v[88:89] op_sel_hi:[0,1]
	ds_read_b128 v[2:5], v94 offset:3456
	v_pk_fma_f32 v[110:111], v[124:125], v[44:45], v[110:111]
	v_pk_fma_f32 v[112:113], v[124:125], v[60:61], v[112:113]
	v_pk_mul_f32 v[128:129], v[70:71], v[90:91] op_sel_hi:[0,1]
	ds_read_b128 v[6:9], v94 offset:3472
	v_pk_fma_f32 v[110:111], v[126:127], v[38:39], v[110:111]
	v_pk_fma_f32 v[112:113], v[126:127], v[54:55], v[112:113]
	ds_read_b128 v[14:17], v94 offset:3488
	v_pk_fma_f32 v[110:111], v[128:129], v[40:41], v[110:111]
	v_pk_fma_f32 v[112:113], v[128:129], v[56:57], v[112:113]
	ds_read_b128 v[10:13], v94 offset:3504
	v_add_f32_e32 v134, v110, v111
	v_add_f32_e32 v135, v112, v113
	ds_read_b32 v73, v95 offset:3712
	v_add_f32_dpp v134, v134, v134 quad_perm:[1,0,3,2] row_mask:0xf bank_mask:0xf bound_ctrl:1
	v_add_f32_dpp v135, v135, v135 quad_perm:[1,0,3,2] row_mask:0xf bank_mask:0xf bound_ctrl:1
	ds_read_b96 v[34:36], v1 offset:3968
	v_add_f32_dpp v134, v134, v134 quad_perm:[2,3,0,1] row_mask:0xf bank_mask:0xf bound_ctrl:1
	v_add_f32_dpp v135, v135, v135 quad_perm:[2,3,0,1] row_mask:0xf bank_mask:0xf bound_ctrl:1
	v_sub_f32_e32 v134, v0, v134
	v_mul_f32_e32 v134, v71, v134
	v_fma_f32 v135, v72, v134, v135
	v_cvt_pk_bf16_f32 v133, v135, v135
	v_pk_fma_f32 v[74:75], v[50:51], v[134:135], v[114:115] op_sel_hi:[1,0,1]
	v_pk_fma_f32 v[78:79], v[52:53], v[134:135], v[116:117] op_sel_hi:[1,0,1]
	global_store_short v147, v133, s[100:101]
	v_pk_fma_f32 v[80:81], v[46:47], v[134:135], v[118:119] op_sel_hi:[1,0,1]
	v_pk_fma_f32 v[82:83], v[48:49], v[134:135], v[120:121] op_sel_hi:[1,0,1]
	v_pk_fma_f32 v[84:85], v[42:43], v[134:135], v[122:123] op_sel_hi:[1,0,1]
	v_pk_fma_f32 v[86:87], v[44:45], v[134:135], v[124:125] op_sel_hi:[1,0,1]
	v_pk_fma_f32 v[88:89], v[38:39], v[134:135], v[126:127] op_sel_hi:[1,0,1]
	v_pk_fma_f32 v[90:91], v[40:41], v[134:135], v[128:129] op_sel_hi:[1,0,1]
	s_waitcnt lgkmcnt(0)
	v_pk_mul_f32 v[114:115], v[34:35], v[74:75] op_sel_hi:[0,1]
	v_pk_mul_f32 v[116:117], v[34:35], v[78:79] op_sel_hi:[0,1]
	v_pk_fma_f32 v[106:107], v[114:115], v[2:3], 0 op_sel_hi:[1,1,0]
	v_pk_fma_f32 v[108:109], v[114:115], v[30:31], 0 op_sel_hi:[1,1,0]
	v_pk_mul_f32 v[118:119], v[34:35], v[80:81] op_sel_hi:[0,1]
	ds_read_b128 v[66:69], v94 offset:4000
	v_pk_fma_f32 v[106:107], v[116:117], v[4:5], v[106:107]
	v_pk_fma_f32 v[108:109], v[116:117], v[32:33], v[108:109]
	v_pk_mul_f32 v[120:121], v[34:35], v[82:83] op_sel_hi:[0,1]
	ds_read_b128 v[62:65], v94 offset:4016
	v_pk_fma_f32 v[106:107], v[118:119], v[6:7], v[106:107]
	v_pk_fma_f32 v[108:109], v[118:119], v[26:27], v[108:109]
	v_pk_mul_f32 v[122:123], v[34:35], v[84:85] op_sel_hi:[0,1]
	ds_read_b128 v[58:61], v94 offset:4032
	v_pk_fma_f32 v[106:107], v[120:121], v[8:9], v[106:107]
	v_pk_fma_f32 v[108:109], v[120:121], v[28:29], v[108:109]
	v_pk_mul_f32 v[124:125], v[34:35], v[86:87] op_sel_hi:[0,1]
	ds_read_b128 v[54:57], v94 offset:4048
	v_pk_fma_f32 v[106:107], v[122:123], v[14:15], v[106:107]
	v_pk_fma_f32 v[108:109], v[122:123], v[22:23], v[108:109]
	v_pk_mul_f32 v[126:127], v[34:35], v[88:89] op_sel_hi:[0,1]
	ds_read_b128 v[50:53], v94 offset:4256
	v_pk_fma_f32 v[106:107], v[124:125], v[16:17], v[106:107]
	v_pk_fma_f32 v[108:109], v[124:125], v[24:25], v[108:109]
	v_pk_mul_f32 v[128:129], v[34:35], v[90:91] op_sel_hi:[0,1]
	ds_read_b128 v[46:49], v94 offset:4272
	v_pk_fma_f32 v[106:107], v[126:127], v[10:11], v[106:107]
	v_pk_fma_f32 v[108:109], v[126:127], v[18:19], v[108:109]
	ds_read_b128 v[42:45], v94 offset:4288
	v_pk_fma_f32 v[106:107], v[128:129], v[12:13], v[106:107]
	v_pk_fma_f32 v[108:109], v[128:129], v[20:21], v[108:109]
	ds_read_b128 v[38:41], v94 offset:4304
	v_add_f32_e32 v130, v106, v107
	v_add_f32_e32 v131, v108, v109
	ds_read_b32 v0, v95 offset:4512
	v_add_f32_dpp v130, v130, v130 quad_perm:[1,0,3,2] row_mask:0xf bank_mask:0xf bound_ctrl:1
	v_add_f32_dpp v131, v131, v131 quad_perm:[1,0,3,2] row_mask:0xf bank_mask:0xf bound_ctrl:1
	ds_read_b96 v[70:72], v1 offset:4768
	v_add_f32_dpp v130, v130, v130 quad_perm:[2,3,0,1] row_mask:0xf bank_mask:0xf bound_ctrl:1
	v_add_f32_dpp v131, v131, v131 quad_perm:[2,3,0,1] row_mask:0xf bank_mask:0xf bound_ctrl:1
	v_sub_f32_e32 v130, v73, v130
	v_mul_f32_e32 v130, v35, v130
	v_fma_f32 v131, v36, v130, v131
	v_cvt_pk_bf16_f32 v132, v131, v131
	v_pk_fma_f32 v[74:75], v[2:3], v[130:131], v[114:115] op_sel_hi:[1,0,1]
	v_pk_fma_f32 v[78:79], v[4:5], v[130:131], v[116:117] op_sel_hi:[1,0,1]
	global_store_short v148, v132, s[100:101]
	v_pk_fma_f32 v[80:81], v[6:7], v[130:131], v[118:119] op_sel_hi:[1,0,1]
	v_pk_fma_f32 v[82:83], v[8:9], v[130:131], v[120:121] op_sel_hi:[1,0,1]
	v_pk_fma_f32 v[84:85], v[14:15], v[130:131], v[122:123] op_sel_hi:[1,0,1]
	v_pk_fma_f32 v[86:87], v[16:17], v[130:131], v[124:125] op_sel_hi:[1,0,1]
	v_pk_fma_f32 v[88:89], v[10:11], v[130:131], v[126:127] op_sel_hi:[1,0,1]
	v_pk_fma_f32 v[90:91], v[12:13], v[130:131], v[128:129] op_sel_hi:[1,0,1]
	s_waitcnt lgkmcnt(0)
	v_pk_mul_f32 v[114:115], v[70:71], v[74:75] op_sel_hi:[0,1]
	v_pk_mul_f32 v[116:117], v[70:71], v[78:79] op_sel_hi:[0,1]
	v_pk_fma_f32 v[110:111], v[114:115], v[50:51], 0 op_sel_hi:[1,1,0]
	v_pk_fma_f32 v[112:113], v[114:115], v[66:67], 0 op_sel_hi:[1,1,0]
	v_pk_mul_f32 v[118:119], v[70:71], v[80:81] op_sel_hi:[0,1]
	ds_read_b128 v[30:33], v94 offset:4800
	v_pk_fma_f32 v[110:111], v[116:117], v[52:53], v[110:111]
	v_pk_fma_f32 v[112:113], v[116:117], v[68:69], v[112:113]
	v_pk_mul_f32 v[120:121], v[70:71], v[82:83] op_sel_hi:[0,1]
	ds_read_b128 v[26:29], v94 offset:4816
	v_pk_fma_f32 v[110:111], v[118:119], v[46:47], v[110:111]
	v_pk_fma_f32 v[112:113], v[118:119], v[62:63], v[112:113]
	v_pk_mul_f32 v[122:123], v[70:71], v[84:85] op_sel_hi:[0,1]
	ds_read_b128 v[22:25], v94 offset:4832
	v_pk_fma_f32 v[110:111], v[120:121], v[48:49], v[110:111]
	v_pk_fma_f32 v[112:113], v[120:121], v[64:65], v[112:113]
	v_pk_mul_f32 v[124:125], v[70:71], v[86:87] op_sel_hi:[0,1]
	ds_read_b128 v[18:21], v94 offset:4848
	v_pk_fma_f32 v[110:111], v[122:123], v[42:43], v[110:111]
	v_pk_fma_f32 v[112:113], v[122:123], v[58:59], v[112:113]
	v_pk_mul_f32 v[126:127], v[70:71], v[88:89] op_sel_hi:[0,1]
	ds_read_b128 v[2:5], v94 offset:5056
	v_pk_fma_f32 v[110:111], v[124:125], v[44:45], v[110:111]
	v_pk_fma_f32 v[112:113], v[124:125], v[60:61], v[112:113]
	v_pk_mul_f32 v[128:129], v[70:71], v[90:91] op_sel_hi:[0,1]
	ds_read_b128 v[6:9], v94 offset:5072
	v_pk_fma_f32 v[110:111], v[126:127], v[38:39], v[110:111]
	v_pk_fma_f32 v[112:113], v[126:127], v[54:55], v[112:113]
	ds_read_b128 v[14:17], v94 offset:5088
	v_pk_fma_f32 v[110:111], v[128:129], v[40:41], v[110:111]
	v_pk_fma_f32 v[112:113], v[128:129], v[56:57], v[112:113]
	ds_read_b128 v[10:13], v94 offset:5104
	v_add_f32_e32 v134, v110, v111
	v_add_f32_e32 v135, v112, v113
	ds_read_b32 v73, v95 offset:5312
	v_add_f32_dpp v134, v134, v134 quad_perm:[1,0,3,2] row_mask:0xf bank_mask:0xf bound_ctrl:1
	v_add_f32_dpp v135, v135, v135 quad_perm:[1,0,3,2] row_mask:0xf bank_mask:0xf bound_ctrl:1
	ds_read_b96 v[34:36], v1 offset:5568
	v_add_f32_dpp v134, v134, v134 quad_perm:[2,3,0,1] row_mask:0xf bank_mask:0xf bound_ctrl:1
	v_add_f32_dpp v135, v135, v135 quad_perm:[2,3,0,1] row_mask:0xf bank_mask:0xf bound_ctrl:1
	v_sub_f32_e32 v134, v0, v134
	v_mul_f32_e32 v134, v71, v134
	v_fma_f32 v135, v72, v134, v135
	v_cvt_pk_bf16_f32 v133, v135, v135
	v_pk_fma_f32 v[74:75], v[50:51], v[134:135], v[114:115] op_sel_hi:[1,0,1]
	v_pk_fma_f32 v[78:79], v[52:53], v[134:135], v[116:117] op_sel_hi:[1,0,1]
	global_store_short v149, v133, s[100:101]
	v_pk_fma_f32 v[80:81], v[46:47], v[134:135], v[118:119] op_sel_hi:[1,0,1]
	v_pk_fma_f32 v[82:83], v[48:49], v[134:135], v[120:121] op_sel_hi:[1,0,1]
	v_pk_fma_f32 v[84:85], v[42:43], v[134:135], v[122:123] op_sel_hi:[1,0,1]
	v_pk_fma_f32 v[86:87], v[44:45], v[134:135], v[124:125] op_sel_hi:[1,0,1]
	v_pk_fma_f32 v[88:89], v[38:39], v[134:135], v[126:127] op_sel_hi:[1,0,1]
	v_pk_fma_f32 v[90:91], v[40:41], v[134:135], v[128:129] op_sel_hi:[1,0,1]
	s_waitcnt lgkmcnt(0)
	v_pk_mul_f32 v[114:115], v[34:35], v[74:75] op_sel_hi:[0,1]
	v_pk_mul_f32 v[116:117], v[34:35], v[78:79] op_sel_hi:[0,1]
	v_pk_fma_f32 v[106:107], v[114:115], v[2:3], 0 op_sel_hi:[1,1,0]
	v_pk_fma_f32 v[108:109], v[114:115], v[30:31], 0 op_sel_hi:[1,1,0]
	v_pk_mul_f32 v[118:119], v[34:35], v[80:81] op_sel_hi:[0,1]
	ds_read_b128 v[66:69], v94 offset:5600
	v_pk_fma_f32 v[106:107], v[116:117], v[4:5], v[106:107]
	v_pk_fma_f32 v[108:109], v[116:117], v[32:33], v[108:109]
	v_pk_mul_f32 v[120:121], v[34:35], v[82:83] op_sel_hi:[0,1]
	ds_read_b128 v[62:65], v94 offset:5616
	v_pk_fma_f32 v[106:107], v[118:119], v[6:7], v[106:107]
	v_pk_fma_f32 v[108:109], v[118:119], v[26:27], v[108:109]
	v_pk_mul_f32 v[122:123], v[34:35], v[84:85] op_sel_hi:[0,1]
	ds_read_b128 v[58:61], v94 offset:5632
	v_pk_fma_f32 v[106:107], v[120:121], v[8:9], v[106:107]
	v_pk_fma_f32 v[108:109], v[120:121], v[28:29], v[108:109]
	v_pk_mul_f32 v[124:125], v[34:35], v[86:87] op_sel_hi:[0,1]
	ds_read_b128 v[54:57], v94 offset:5648
	v_pk_fma_f32 v[106:107], v[122:123], v[14:15], v[106:107]
	v_pk_fma_f32 v[108:109], v[122:123], v[22:23], v[108:109]
	v_pk_mul_f32 v[126:127], v[34:35], v[88:89] op_sel_hi:[0,1]
	ds_read_b128 v[50:53], v94 offset:5856
	v_pk_fma_f32 v[106:107], v[124:125], v[16:17], v[106:107]
	v_pk_fma_f32 v[108:109], v[124:125], v[24:25], v[108:109]
	v_pk_mul_f32 v[128:129], v[34:35], v[90:91] op_sel_hi:[0,1]
	ds_read_b128 v[46:49], v94 offset:5872
	v_pk_fma_f32 v[106:107], v[126:127], v[10:11], v[106:107]
	v_pk_fma_f32 v[108:109], v[126:127], v[18:19], v[108:109]
	ds_read_b128 v[42:45], v94 offset:5888
	v_pk_fma_f32 v[106:107], v[128:129], v[12:13], v[106:107]
	v_pk_fma_f32 v[108:109], v[128:129], v[20:21], v[108:109]
	ds_read_b128 v[38:41], v94 offset:5904
	v_add_f32_e32 v130, v106, v107
	v_add_f32_e32 v131, v108, v109
	ds_read_b32 v0, v95 offset:6112
	v_add_f32_dpp v130, v130, v130 quad_perm:[1,0,3,2] row_mask:0xf bank_mask:0xf bound_ctrl:1
	v_add_f32_dpp v131, v131, v131 quad_perm:[1,0,3,2] row_mask:0xf bank_mask:0xf bound_ctrl:1
	ds_read_b96 v[70:72], v1 offset:6368
	v_add_f32_dpp v130, v130, v130 quad_perm:[2,3,0,1] row_mask:0xf bank_mask:0xf bound_ctrl:1
	v_add_f32_dpp v131, v131, v131 quad_perm:[2,3,0,1] row_mask:0xf bank_mask:0xf bound_ctrl:1
	v_sub_f32_e32 v130, v73, v130
	v_mul_f32_e32 v130, v35, v130
	v_fma_f32 v131, v36, v130, v131
	v_cvt_pk_bf16_f32 v132, v131, v131
	v_pk_fma_f32 v[74:75], v[2:3], v[130:131], v[114:115] op_sel_hi:[1,0,1]
	v_pk_fma_f32 v[78:79], v[4:5], v[130:131], v[116:117] op_sel_hi:[1,0,1]
	global_store_short v150, v132, s[100:101]
	v_pk_fma_f32 v[80:81], v[6:7], v[130:131], v[118:119] op_sel_hi:[1,0,1]
	v_pk_fma_f32 v[82:83], v[8:9], v[130:131], v[120:121] op_sel_hi:[1,0,1]
	v_pk_fma_f32 v[84:85], v[14:15], v[130:131], v[122:123] op_sel_hi:[1,0,1]
	v_pk_fma_f32 v[86:87], v[16:17], v[130:131], v[124:125] op_sel_hi:[1,0,1]
	v_pk_fma_f32 v[88:89], v[10:11], v[130:131], v[126:127] op_sel_hi:[1,0,1]
	v_pk_fma_f32 v[90:91], v[12:13], v[130:131], v[128:129] op_sel_hi:[1,0,1]
	s_waitcnt lgkmcnt(0)
	v_pk_mul_f32 v[114:115], v[70:71], v[74:75] op_sel_hi:[0,1]
	v_pk_mul_f32 v[116:117], v[70:71], v[78:79] op_sel_hi:[0,1]
	v_pk_fma_f32 v[110:111], v[114:115], v[50:51], 0 op_sel_hi:[1,1,0]
	v_pk_fma_f32 v[112:113], v[114:115], v[66:67], 0 op_sel_hi:[1,1,0]
	v_pk_mul_f32 v[118:119], v[70:71], v[80:81] op_sel_hi:[0,1]
	ds_read_b128 v[30:33], v94 offset:6400
	v_pk_fma_f32 v[110:111], v[116:117], v[52:53], v[110:111]
	v_pk_fma_f32 v[112:113], v[116:117], v[68:69], v[112:113]
	v_pk_mul_f32 v[120:121], v[70:71], v[82:83] op_sel_hi:[0,1]
	ds_read_b128 v[26:29], v94 offset:6416
	v_pk_fma_f32 v[110:111], v[118:119], v[46:47], v[110:111]
	v_pk_fma_f32 v[112:113], v[118:119], v[62:63], v[112:113]
	v_pk_mul_f32 v[122:123], v[70:71], v[84:85] op_sel_hi:[0,1]
	ds_read_b128 v[22:25], v94 offset:6432
	v_pk_fma_f32 v[110:111], v[120:121], v[48:49], v[110:111]
	v_pk_fma_f32 v[112:113], v[120:121], v[64:65], v[112:113]
	v_pk_mul_f32 v[124:125], v[70:71], v[86:87] op_sel_hi:[0,1]
	ds_read_b128 v[18:21], v94 offset:6448
	v_pk_fma_f32 v[110:111], v[122:123], v[42:43], v[110:111]
	v_pk_fma_f32 v[112:113], v[122:123], v[58:59], v[112:113]
	v_pk_mul_f32 v[126:127], v[70:71], v[88:89] op_sel_hi:[0,1]
	ds_read_b128 v[2:5], v94 offset:6656
	v_pk_fma_f32 v[110:111], v[124:125], v[44:45], v[110:111]
	v_pk_fma_f32 v[112:113], v[124:125], v[60:61], v[112:113]
	v_pk_mul_f32 v[128:129], v[70:71], v[90:91] op_sel_hi:[0,1]
	ds_read_b128 v[6:9], v94 offset:6672
	v_pk_fma_f32 v[110:111], v[126:127], v[38:39], v[110:111]
	v_pk_fma_f32 v[112:113], v[126:127], v[54:55], v[112:113]
	ds_read_b128 v[14:17], v94 offset:6688
	v_pk_fma_f32 v[110:111], v[128:129], v[40:41], v[110:111]
	v_pk_fma_f32 v[112:113], v[128:129], v[56:57], v[112:113]
	ds_read_b128 v[10:13], v94 offset:6704
	v_add_f32_e32 v134, v110, v111
	v_add_f32_e32 v135, v112, v113
	ds_read_b32 v73, v95 offset:6912
	v_add_f32_dpp v134, v134, v134 quad_perm:[1,0,3,2] row_mask:0xf bank_mask:0xf bound_ctrl:1
	v_add_f32_dpp v135, v135, v135 quad_perm:[1,0,3,2] row_mask:0xf bank_mask:0xf bound_ctrl:1
	ds_read_b96 v[34:36], v1 offset:7168
	v_add_f32_dpp v134, v134, v134 quad_perm:[2,3,0,1] row_mask:0xf bank_mask:0xf bound_ctrl:1
	v_add_f32_dpp v135, v135, v135 quad_perm:[2,3,0,1] row_mask:0xf bank_mask:0xf bound_ctrl:1
	v_sub_f32_e32 v134, v0, v134
	v_mul_f32_e32 v134, v71, v134
	v_fma_f32 v135, v72, v134, v135
	v_cvt_pk_bf16_f32 v133, v135, v135
	v_pk_fma_f32 v[74:75], v[50:51], v[134:135], v[114:115] op_sel_hi:[1,0,1]
	v_pk_fma_f32 v[78:79], v[52:53], v[134:135], v[116:117] op_sel_hi:[1,0,1]
	global_store_short v151, v133, s[100:101]
	v_pk_fma_f32 v[80:81], v[46:47], v[134:135], v[118:119] op_sel_hi:[1,0,1]
	v_pk_fma_f32 v[82:83], v[48:49], v[134:135], v[120:121] op_sel_hi:[1,0,1]
	v_pk_fma_f32 v[84:85], v[42:43], v[134:135], v[122:123] op_sel_hi:[1,0,1]
	v_pk_fma_f32 v[86:87], v[44:45], v[134:135], v[124:125] op_sel_hi:[1,0,1]
	v_pk_fma_f32 v[88:89], v[38:39], v[134:135], v[126:127] op_sel_hi:[1,0,1]
	v_pk_fma_f32 v[90:91], v[40:41], v[134:135], v[128:129] op_sel_hi:[1,0,1]
	s_waitcnt lgkmcnt(0)
	v_pk_mul_f32 v[114:115], v[34:35], v[74:75] op_sel_hi:[0,1]
	v_pk_mul_f32 v[116:117], v[34:35], v[78:79] op_sel_hi:[0,1]
	v_pk_fma_f32 v[106:107], v[114:115], v[2:3], 0 op_sel_hi:[1,1,0]
	v_pk_fma_f32 v[108:109], v[114:115], v[30:31], 0 op_sel_hi:[1,1,0]
	v_pk_mul_f32 v[118:119], v[34:35], v[80:81] op_sel_hi:[0,1]
	ds_read_b128 v[66:69], v94 offset:7200
	v_pk_fma_f32 v[106:107], v[116:117], v[4:5], v[106:107]
	v_pk_fma_f32 v[108:109], v[116:117], v[32:33], v[108:109]
	v_pk_mul_f32 v[120:121], v[34:35], v[82:83] op_sel_hi:[0,1]
	ds_read_b128 v[62:65], v94 offset:7216
	v_pk_fma_f32 v[106:107], v[118:119], v[6:7], v[106:107]
	v_pk_fma_f32 v[108:109], v[118:119], v[26:27], v[108:109]
	v_pk_mul_f32 v[122:123], v[34:35], v[84:85] op_sel_hi:[0,1]
	ds_read_b128 v[58:61], v94 offset:7232
	v_pk_fma_f32 v[106:107], v[120:121], v[8:9], v[106:107]
	v_pk_fma_f32 v[108:109], v[120:121], v[28:29], v[108:109]
	v_pk_mul_f32 v[124:125], v[34:35], v[86:87] op_sel_hi:[0,1]
	ds_read_b128 v[54:57], v94 offset:7248
	v_pk_fma_f32 v[106:107], v[122:123], v[14:15], v[106:107]
	v_pk_fma_f32 v[108:109], v[122:123], v[22:23], v[108:109]
	v_pk_mul_f32 v[126:127], v[34:35], v[88:89] op_sel_hi:[0,1]
	ds_read_b128 v[50:53], v94 offset:7456
	v_pk_fma_f32 v[106:107], v[124:125], v[16:17], v[106:107]
	v_pk_fma_f32 v[108:109], v[124:125], v[24:25], v[108:109]
	v_pk_mul_f32 v[128:129], v[34:35], v[90:91] op_sel_hi:[0,1]
	ds_read_b128 v[46:49], v94 offset:7472
	v_pk_fma_f32 v[106:107], v[126:127], v[10:11], v[106:107]
	v_pk_fma_f32 v[108:109], v[126:127], v[18:19], v[108:109]
	ds_read_b128 v[42:45], v94 offset:7488
	v_pk_fma_f32 v[106:107], v[128:129], v[12:13], v[106:107]
	v_pk_fma_f32 v[108:109], v[128:129], v[20:21], v[108:109]
	ds_read_b128 v[38:41], v94 offset:7504
	v_add_f32_e32 v130, v106, v107
	v_add_f32_e32 v131, v108, v109
	ds_read_b32 v0, v95 offset:7712
	v_add_f32_dpp v130, v130, v130 quad_perm:[1,0,3,2] row_mask:0xf bank_mask:0xf bound_ctrl:1
	v_add_f32_dpp v131, v131, v131 quad_perm:[1,0,3,2] row_mask:0xf bank_mask:0xf bound_ctrl:1
	ds_read_b96 v[70:72], v1 offset:7968
	v_add_f32_dpp v130, v130, v130 quad_perm:[2,3,0,1] row_mask:0xf bank_mask:0xf bound_ctrl:1
	v_add_f32_dpp v131, v131, v131 quad_perm:[2,3,0,1] row_mask:0xf bank_mask:0xf bound_ctrl:1
	v_sub_f32_e32 v130, v73, v130
	v_mul_f32_e32 v130, v35, v130
	v_fma_f32 v131, v36, v130, v131
	v_cvt_pk_bf16_f32 v132, v131, v131
	v_pk_fma_f32 v[74:75], v[2:3], v[130:131], v[114:115] op_sel_hi:[1,0,1]
	v_pk_fma_f32 v[78:79], v[4:5], v[130:131], v[116:117] op_sel_hi:[1,0,1]
	global_store_short v152, v132, s[100:101]
	v_pk_fma_f32 v[80:81], v[6:7], v[130:131], v[118:119] op_sel_hi:[1,0,1]
	v_pk_fma_f32 v[82:83], v[8:9], v[130:131], v[120:121] op_sel_hi:[1,0,1]
	v_pk_fma_f32 v[84:85], v[14:15], v[130:131], v[122:123] op_sel_hi:[1,0,1]
	v_pk_fma_f32 v[86:87], v[16:17], v[130:131], v[124:125] op_sel_hi:[1,0,1]
	v_pk_fma_f32 v[88:89], v[10:11], v[130:131], v[126:127] op_sel_hi:[1,0,1]
	v_pk_fma_f32 v[90:91], v[12:13], v[130:131], v[128:129] op_sel_hi:[1,0,1]
	s_waitcnt lgkmcnt(0)
	v_pk_mul_f32 v[114:115], v[70:71], v[74:75] op_sel_hi:[0,1]
	v_pk_mul_f32 v[116:117], v[70:71], v[78:79] op_sel_hi:[0,1]
	v_pk_fma_f32 v[110:111], v[114:115], v[50:51], 0 op_sel_hi:[1,1,0]
	v_pk_fma_f32 v[112:113], v[114:115], v[66:67], 0 op_sel_hi:[1,1,0]
	v_pk_mul_f32 v[118:119], v[70:71], v[80:81] op_sel_hi:[0,1]
	ds_read_b128 v[30:33], v94 offset:8000
	v_pk_fma_f32 v[110:111], v[116:117], v[52:53], v[110:111]
	v_pk_fma_f32 v[112:113], v[116:117], v[68:69], v[112:113]
	v_pk_mul_f32 v[120:121], v[70:71], v[82:83] op_sel_hi:[0,1]
	ds_read_b128 v[26:29], v94 offset:8016
	v_pk_fma_f32 v[110:111], v[118:119], v[46:47], v[110:111]
	v_pk_fma_f32 v[112:113], v[118:119], v[62:63], v[112:113]
	v_pk_mul_f32 v[122:123], v[70:71], v[84:85] op_sel_hi:[0,1]
	ds_read_b128 v[22:25], v94 offset:8032
	v_pk_fma_f32 v[110:111], v[120:121], v[48:49], v[110:111]
	v_pk_fma_f32 v[112:113], v[120:121], v[64:65], v[112:113]
	v_pk_mul_f32 v[124:125], v[70:71], v[86:87] op_sel_hi:[0,1]
	ds_read_b128 v[18:21], v94 offset:8048
	v_pk_fma_f32 v[110:111], v[122:123], v[42:43], v[110:111]
	v_pk_fma_f32 v[112:113], v[122:123], v[58:59], v[112:113]
	v_pk_mul_f32 v[126:127], v[70:71], v[88:89] op_sel_hi:[0,1]
	ds_read_b128 v[2:5], v94 offset:8256
	v_pk_fma_f32 v[110:111], v[124:125], v[44:45], v[110:111]
	v_pk_fma_f32 v[112:113], v[124:125], v[60:61], v[112:113]
	v_pk_mul_f32 v[128:129], v[70:71], v[90:91] op_sel_hi:[0,1]
	ds_read_b128 v[6:9], v94 offset:8272
	v_pk_fma_f32 v[110:111], v[126:127], v[38:39], v[110:111]
	v_pk_fma_f32 v[112:113], v[126:127], v[54:55], v[112:113]
	ds_read_b128 v[14:17], v94 offset:8288
	v_pk_fma_f32 v[110:111], v[128:129], v[40:41], v[110:111]
	v_pk_fma_f32 v[112:113], v[128:129], v[56:57], v[112:113]
	ds_read_b128 v[10:13], v94 offset:8304
	v_add_f32_e32 v134, v110, v111
	v_add_f32_e32 v135, v112, v113
	ds_read_b32 v73, v95 offset:8512
	v_add_f32_dpp v134, v134, v134 quad_perm:[1,0,3,2] row_mask:0xf bank_mask:0xf bound_ctrl:1
	v_add_f32_dpp v135, v135, v135 quad_perm:[1,0,3,2] row_mask:0xf bank_mask:0xf bound_ctrl:1
	ds_read_b96 v[34:36], v1 offset:8768
	v_add_f32_dpp v134, v134, v134 quad_perm:[2,3,0,1] row_mask:0xf bank_mask:0xf bound_ctrl:1
	v_add_f32_dpp v135, v135, v135 quad_perm:[2,3,0,1] row_mask:0xf bank_mask:0xf bound_ctrl:1
	v_sub_f32_e32 v134, v0, v134
	v_mul_f32_e32 v134, v71, v134
	v_fma_f32 v135, v72, v134, v135
	v_cvt_pk_bf16_f32 v133, v135, v135
	v_pk_fma_f32 v[74:75], v[50:51], v[134:135], v[114:115] op_sel_hi:[1,0,1]
	v_pk_fma_f32 v[78:79], v[52:53], v[134:135], v[116:117] op_sel_hi:[1,0,1]
	global_store_short v153, v133, s[100:101]
	v_pk_fma_f32 v[80:81], v[46:47], v[134:135], v[118:119] op_sel_hi:[1,0,1]
	v_pk_fma_f32 v[82:83], v[48:49], v[134:135], v[120:121] op_sel_hi:[1,0,1]
	v_pk_fma_f32 v[84:85], v[42:43], v[134:135], v[122:123] op_sel_hi:[1,0,1]
	v_pk_fma_f32 v[86:87], v[44:45], v[134:135], v[124:125] op_sel_hi:[1,0,1]
	v_pk_fma_f32 v[88:89], v[38:39], v[134:135], v[126:127] op_sel_hi:[1,0,1]
	v_pk_fma_f32 v[90:91], v[40:41], v[134:135], v[128:129] op_sel_hi:[1,0,1]
	s_waitcnt lgkmcnt(0)
	v_pk_mul_f32 v[114:115], v[34:35], v[74:75] op_sel_hi:[0,1]
	v_pk_mul_f32 v[116:117], v[34:35], v[78:79] op_sel_hi:[0,1]
	v_pk_fma_f32 v[106:107], v[114:115], v[2:3], 0 op_sel_hi:[1,1,0]
	v_pk_fma_f32 v[108:109], v[114:115], v[30:31], 0 op_sel_hi:[1,1,0]
	v_pk_mul_f32 v[118:119], v[34:35], v[80:81] op_sel_hi:[0,1]
	ds_read_b128 v[66:69], v94 offset:8800
	v_pk_fma_f32 v[106:107], v[116:117], v[4:5], v[106:107]
	v_pk_fma_f32 v[108:109], v[116:117], v[32:33], v[108:109]
	v_pk_mul_f32 v[120:121], v[34:35], v[82:83] op_sel_hi:[0,1]
	ds_read_b128 v[62:65], v94 offset:8816
	v_pk_fma_f32 v[106:107], v[118:119], v[6:7], v[106:107]
	v_pk_fma_f32 v[108:109], v[118:119], v[26:27], v[108:109]
	v_pk_mul_f32 v[122:123], v[34:35], v[84:85] op_sel_hi:[0,1]
	ds_read_b128 v[58:61], v94 offset:8832
	v_pk_fma_f32 v[106:107], v[120:121], v[8:9], v[106:107]
	v_pk_fma_f32 v[108:109], v[120:121], v[28:29], v[108:109]
	v_pk_mul_f32 v[124:125], v[34:35], v[86:87] op_sel_hi:[0,1]
	ds_read_b128 v[54:57], v94 offset:8848
	v_pk_fma_f32 v[106:107], v[122:123], v[14:15], v[106:107]
	v_pk_fma_f32 v[108:109], v[122:123], v[22:23], v[108:109]
	v_pk_mul_f32 v[126:127], v[34:35], v[88:89] op_sel_hi:[0,1]
	ds_read_b128 v[50:53], v94 offset:9056
	v_pk_fma_f32 v[106:107], v[124:125], v[16:17], v[106:107]
	v_pk_fma_f32 v[108:109], v[124:125], v[24:25], v[108:109]
	v_pk_mul_f32 v[128:129], v[34:35], v[90:91] op_sel_hi:[0,1]
	ds_read_b128 v[46:49], v94 offset:9072
	v_pk_fma_f32 v[106:107], v[126:127], v[10:11], v[106:107]
	v_pk_fma_f32 v[108:109], v[126:127], v[18:19], v[108:109]
	ds_read_b128 v[42:45], v94 offset:9088
	v_pk_fma_f32 v[106:107], v[128:129], v[12:13], v[106:107]
	v_pk_fma_f32 v[108:109], v[128:129], v[20:21], v[108:109]
	ds_read_b128 v[38:41], v94 offset:9104
	v_add_f32_e32 v130, v106, v107
	v_add_f32_e32 v131, v108, v109
	ds_read_b32 v0, v95 offset:9312
	v_add_f32_dpp v130, v130, v130 quad_perm:[1,0,3,2] row_mask:0xf bank_mask:0xf bound_ctrl:1
	v_add_f32_dpp v131, v131, v131 quad_perm:[1,0,3,2] row_mask:0xf bank_mask:0xf bound_ctrl:1
	ds_read_b96 v[70:72], v1 offset:9568
	v_add_f32_dpp v130, v130, v130 quad_perm:[2,3,0,1] row_mask:0xf bank_mask:0xf bound_ctrl:1
	v_add_f32_dpp v131, v131, v131 quad_perm:[2,3,0,1] row_mask:0xf bank_mask:0xf bound_ctrl:1
	v_sub_f32_e32 v130, v73, v130
	v_mul_f32_e32 v130, v35, v130
	v_fma_f32 v131, v36, v130, v131
	v_cvt_pk_bf16_f32 v132, v131, v131
	v_pk_fma_f32 v[74:75], v[2:3], v[130:131], v[114:115] op_sel_hi:[1,0,1]
	v_pk_fma_f32 v[78:79], v[4:5], v[130:131], v[116:117] op_sel_hi:[1,0,1]
	global_store_short v154, v132, s[100:101]
	v_pk_fma_f32 v[80:81], v[6:7], v[130:131], v[118:119] op_sel_hi:[1,0,1]
	v_pk_fma_f32 v[82:83], v[8:9], v[130:131], v[120:121] op_sel_hi:[1,0,1]
	v_pk_fma_f32 v[84:85], v[14:15], v[130:131], v[122:123] op_sel_hi:[1,0,1]
	v_pk_fma_f32 v[86:87], v[16:17], v[130:131], v[124:125] op_sel_hi:[1,0,1]
	v_pk_fma_f32 v[88:89], v[10:11], v[130:131], v[126:127] op_sel_hi:[1,0,1]
	v_pk_fma_f32 v[90:91], v[12:13], v[130:131], v[128:129] op_sel_hi:[1,0,1]
	s_waitcnt lgkmcnt(0)
	v_pk_mul_f32 v[114:115], v[70:71], v[74:75] op_sel_hi:[0,1]
	v_pk_mul_f32 v[116:117], v[70:71], v[78:79] op_sel_hi:[0,1]
	v_pk_fma_f32 v[110:111], v[114:115], v[50:51], 0 op_sel_hi:[1,1,0]
	v_pk_fma_f32 v[112:113], v[114:115], v[66:67], 0 op_sel_hi:[1,1,0]
	v_pk_mul_f32 v[118:119], v[70:71], v[80:81] op_sel_hi:[0,1]
	ds_read_b128 v[30:33], v94 offset:9600
	v_pk_fma_f32 v[110:111], v[116:117], v[52:53], v[110:111]
	v_pk_fma_f32 v[112:113], v[116:117], v[68:69], v[112:113]
	v_pk_mul_f32 v[120:121], v[70:71], v[82:83] op_sel_hi:[0,1]
	ds_read_b128 v[26:29], v94 offset:9616
	v_pk_fma_f32 v[110:111], v[118:119], v[46:47], v[110:111]
	v_pk_fma_f32 v[112:113], v[118:119], v[62:63], v[112:113]
	v_pk_mul_f32 v[122:123], v[70:71], v[84:85] op_sel_hi:[0,1]
	ds_read_b128 v[22:25], v94 offset:9632
	v_pk_fma_f32 v[110:111], v[120:121], v[48:49], v[110:111]
	v_pk_fma_f32 v[112:113], v[120:121], v[64:65], v[112:113]
	v_pk_mul_f32 v[124:125], v[70:71], v[86:87] op_sel_hi:[0,1]
	ds_read_b128 v[18:21], v94 offset:9648
	v_pk_fma_f32 v[110:111], v[122:123], v[42:43], v[110:111]
	v_pk_fma_f32 v[112:113], v[122:123], v[58:59], v[112:113]
	v_pk_mul_f32 v[126:127], v[70:71], v[88:89] op_sel_hi:[0,1]
	ds_read_b128 v[2:5], v94 offset:9856
	v_pk_fma_f32 v[110:111], v[124:125], v[44:45], v[110:111]
	v_pk_fma_f32 v[112:113], v[124:125], v[60:61], v[112:113]
	v_pk_mul_f32 v[128:129], v[70:71], v[90:91] op_sel_hi:[0,1]
	ds_read_b128 v[6:9], v94 offset:9872
	v_pk_fma_f32 v[110:111], v[126:127], v[38:39], v[110:111]
	v_pk_fma_f32 v[112:113], v[126:127], v[54:55], v[112:113]
	ds_read_b128 v[14:17], v94 offset:9888
	v_pk_fma_f32 v[110:111], v[128:129], v[40:41], v[110:111]
	v_pk_fma_f32 v[112:113], v[128:129], v[56:57], v[112:113]
	ds_read_b128 v[10:13], v94 offset:9904
	v_add_f32_e32 v134, v110, v111
	v_add_f32_e32 v135, v112, v113
	ds_read_b32 v73, v95 offset:10112
	v_add_f32_dpp v134, v134, v134 quad_perm:[1,0,3,2] row_mask:0xf bank_mask:0xf bound_ctrl:1
	v_add_f32_dpp v135, v135, v135 quad_perm:[1,0,3,2] row_mask:0xf bank_mask:0xf bound_ctrl:1
	ds_read_b96 v[34:36], v1 offset:10368
	v_add_f32_dpp v134, v134, v134 quad_perm:[2,3,0,1] row_mask:0xf bank_mask:0xf bound_ctrl:1
	v_add_f32_dpp v135, v135, v135 quad_perm:[2,3,0,1] row_mask:0xf bank_mask:0xf bound_ctrl:1
	v_sub_f32_e32 v134, v0, v134
	v_mul_f32_e32 v134, v71, v134
	v_fma_f32 v135, v72, v134, v135
	v_cvt_pk_bf16_f32 v133, v135, v135
	v_pk_fma_f32 v[74:75], v[50:51], v[134:135], v[114:115] op_sel_hi:[1,0,1]
	v_pk_fma_f32 v[78:79], v[52:53], v[134:135], v[116:117] op_sel_hi:[1,0,1]
	global_store_short v155, v133, s[100:101]
	v_pk_fma_f32 v[80:81], v[46:47], v[134:135], v[118:119] op_sel_hi:[1,0,1]
	v_pk_fma_f32 v[82:83], v[48:49], v[134:135], v[120:121] op_sel_hi:[1,0,1]
	v_pk_fma_f32 v[84:85], v[42:43], v[134:135], v[122:123] op_sel_hi:[1,0,1]
	v_pk_fma_f32 v[86:87], v[44:45], v[134:135], v[124:125] op_sel_hi:[1,0,1]
	v_pk_fma_f32 v[88:89], v[38:39], v[134:135], v[126:127] op_sel_hi:[1,0,1]
	v_pk_fma_f32 v[90:91], v[40:41], v[134:135], v[128:129] op_sel_hi:[1,0,1]
	s_waitcnt lgkmcnt(0)
	v_pk_mul_f32 v[114:115], v[34:35], v[74:75] op_sel_hi:[0,1]
	v_pk_mul_f32 v[116:117], v[34:35], v[78:79] op_sel_hi:[0,1]
	v_pk_fma_f32 v[106:107], v[114:115], v[2:3], 0 op_sel_hi:[1,1,0]
	v_pk_fma_f32 v[108:109], v[114:115], v[30:31], 0 op_sel_hi:[1,1,0]
	v_pk_mul_f32 v[118:119], v[34:35], v[80:81] op_sel_hi:[0,1]
	ds_read_b128 v[66:69], v94 offset:10400
	v_pk_fma_f32 v[106:107], v[116:117], v[4:5], v[106:107]
	v_pk_fma_f32 v[108:109], v[116:117], v[32:33], v[108:109]
	v_pk_mul_f32 v[120:121], v[34:35], v[82:83] op_sel_hi:[0,1]
	ds_read_b128 v[62:65], v94 offset:10416
	v_pk_fma_f32 v[106:107], v[118:119], v[6:7], v[106:107]
	v_pk_fma_f32 v[108:109], v[118:119], v[26:27], v[108:109]
	v_pk_mul_f32 v[122:123], v[34:35], v[84:85] op_sel_hi:[0,1]
	ds_read_b128 v[58:61], v94 offset:10432
	v_pk_fma_f32 v[106:107], v[120:121], v[8:9], v[106:107]
	v_pk_fma_f32 v[108:109], v[120:121], v[28:29], v[108:109]
	v_pk_mul_f32 v[124:125], v[34:35], v[86:87] op_sel_hi:[0,1]
	ds_read_b128 v[54:57], v94 offset:10448
	v_pk_fma_f32 v[106:107], v[122:123], v[14:15], v[106:107]
	v_pk_fma_f32 v[108:109], v[122:123], v[22:23], v[108:109]
	v_pk_mul_f32 v[126:127], v[34:35], v[88:89] op_sel_hi:[0,1]
	ds_read_b128 v[50:53], v94 offset:10656
	v_pk_fma_f32 v[106:107], v[124:125], v[16:17], v[106:107]
	v_pk_fma_f32 v[108:109], v[124:125], v[24:25], v[108:109]
	v_pk_mul_f32 v[128:129], v[34:35], v[90:91] op_sel_hi:[0,1]
	ds_read_b128 v[46:49], v94 offset:10672
	v_pk_fma_f32 v[106:107], v[126:127], v[10:11], v[106:107]
	v_pk_fma_f32 v[108:109], v[126:127], v[18:19], v[108:109]
	ds_read_b128 v[42:45], v94 offset:10688
	v_pk_fma_f32 v[106:107], v[128:129], v[12:13], v[106:107]
	v_pk_fma_f32 v[108:109], v[128:129], v[20:21], v[108:109]
	ds_read_b128 v[38:41], v94 offset:10704
	v_add_f32_e32 v130, v106, v107
	v_add_f32_e32 v131, v108, v109
	ds_read_b32 v0, v95 offset:10912
	v_add_f32_dpp v130, v130, v130 quad_perm:[1,0,3,2] row_mask:0xf bank_mask:0xf bound_ctrl:1
	v_add_f32_dpp v131, v131, v131 quad_perm:[1,0,3,2] row_mask:0xf bank_mask:0xf bound_ctrl:1
	ds_read_b96 v[70:72], v1 offset:11168
	v_add_f32_dpp v130, v130, v130 quad_perm:[2,3,0,1] row_mask:0xf bank_mask:0xf bound_ctrl:1
	v_add_f32_dpp v131, v131, v131 quad_perm:[2,3,0,1] row_mask:0xf bank_mask:0xf bound_ctrl:1
	v_sub_f32_e32 v130, v73, v130
	v_mul_f32_e32 v130, v35, v130
	v_fma_f32 v131, v36, v130, v131
	v_cvt_pk_bf16_f32 v132, v131, v131
	v_pk_fma_f32 v[74:75], v[2:3], v[130:131], v[114:115] op_sel_hi:[1,0,1]
	v_pk_fma_f32 v[78:79], v[4:5], v[130:131], v[116:117] op_sel_hi:[1,0,1]
	global_store_short v156, v132, s[100:101]
	v_pk_fma_f32 v[80:81], v[6:7], v[130:131], v[118:119] op_sel_hi:[1,0,1]
	v_pk_fma_f32 v[82:83], v[8:9], v[130:131], v[120:121] op_sel_hi:[1,0,1]
	v_pk_fma_f32 v[84:85], v[14:15], v[130:131], v[122:123] op_sel_hi:[1,0,1]
	v_pk_fma_f32 v[86:87], v[16:17], v[130:131], v[124:125] op_sel_hi:[1,0,1]
	v_pk_fma_f32 v[88:89], v[10:11], v[130:131], v[126:127] op_sel_hi:[1,0,1]
	v_pk_fma_f32 v[90:91], v[12:13], v[130:131], v[128:129] op_sel_hi:[1,0,1]
	s_waitcnt lgkmcnt(0)
	v_pk_mul_f32 v[114:115], v[70:71], v[74:75] op_sel_hi:[0,1]
	v_pk_mul_f32 v[116:117], v[70:71], v[78:79] op_sel_hi:[0,1]
	v_pk_fma_f32 v[110:111], v[114:115], v[50:51], 0 op_sel_hi:[1,1,0]
	v_pk_fma_f32 v[112:113], v[114:115], v[66:67], 0 op_sel_hi:[1,1,0]
	v_pk_mul_f32 v[118:119], v[70:71], v[80:81] op_sel_hi:[0,1]
	ds_read_b128 v[30:33], v94 offset:11200
	v_pk_fma_f32 v[110:111], v[116:117], v[52:53], v[110:111]
	v_pk_fma_f32 v[112:113], v[116:117], v[68:69], v[112:113]
	v_pk_mul_f32 v[120:121], v[70:71], v[82:83] op_sel_hi:[0,1]
	ds_read_b128 v[26:29], v94 offset:11216
	v_pk_fma_f32 v[110:111], v[118:119], v[46:47], v[110:111]
	v_pk_fma_f32 v[112:113], v[118:119], v[62:63], v[112:113]
	v_pk_mul_f32 v[122:123], v[70:71], v[84:85] op_sel_hi:[0,1]
	ds_read_b128 v[22:25], v94 offset:11232
	v_pk_fma_f32 v[110:111], v[120:121], v[48:49], v[110:111]
	v_pk_fma_f32 v[112:113], v[120:121], v[64:65], v[112:113]
	v_pk_mul_f32 v[124:125], v[70:71], v[86:87] op_sel_hi:[0,1]
	ds_read_b128 v[18:21], v94 offset:11248
	v_pk_fma_f32 v[110:111], v[122:123], v[42:43], v[110:111]
	v_pk_fma_f32 v[112:113], v[122:123], v[58:59], v[112:113]
	v_pk_mul_f32 v[126:127], v[70:71], v[88:89] op_sel_hi:[0,1]
	ds_read_b128 v[2:5], v94 offset:11456
	v_pk_fma_f32 v[110:111], v[124:125], v[44:45], v[110:111]
	v_pk_fma_f32 v[112:113], v[124:125], v[60:61], v[112:113]
	v_pk_mul_f32 v[128:129], v[70:71], v[90:91] op_sel_hi:[0,1]
	ds_read_b128 v[6:9], v94 offset:11472
	v_pk_fma_f32 v[110:111], v[126:127], v[38:39], v[110:111]
	v_pk_fma_f32 v[112:113], v[126:127], v[54:55], v[112:113]
	ds_read_b128 v[14:17], v94 offset:11488
	v_pk_fma_f32 v[110:111], v[128:129], v[40:41], v[110:111]
	v_pk_fma_f32 v[112:113], v[128:129], v[56:57], v[112:113]
	ds_read_b128 v[10:13], v94 offset:11504
	v_add_f32_e32 v134, v110, v111
	v_add_f32_e32 v135, v112, v113
	ds_read_b32 v73, v95 offset:11712
	v_add_f32_dpp v134, v134, v134 quad_perm:[1,0,3,2] row_mask:0xf bank_mask:0xf bound_ctrl:1
	v_add_f32_dpp v135, v135, v135 quad_perm:[1,0,3,2] row_mask:0xf bank_mask:0xf bound_ctrl:1
	ds_read_b96 v[34:36], v1 offset:11968
	v_add_f32_dpp v134, v134, v134 quad_perm:[2,3,0,1] row_mask:0xf bank_mask:0xf bound_ctrl:1
	v_add_f32_dpp v135, v135, v135 quad_perm:[2,3,0,1] row_mask:0xf bank_mask:0xf bound_ctrl:1
	v_sub_f32_e32 v134, v0, v134
	v_mul_f32_e32 v134, v71, v134
	v_fma_f32 v135, v72, v134, v135
	v_cvt_pk_bf16_f32 v133, v135, v135
	v_pk_fma_f32 v[74:75], v[50:51], v[134:135], v[114:115] op_sel_hi:[1,0,1]
	v_pk_fma_f32 v[78:79], v[52:53], v[134:135], v[116:117] op_sel_hi:[1,0,1]
	global_store_short v157, v133, s[100:101]
	v_pk_fma_f32 v[80:81], v[46:47], v[134:135], v[118:119] op_sel_hi:[1,0,1]
	v_pk_fma_f32 v[82:83], v[48:49], v[134:135], v[120:121] op_sel_hi:[1,0,1]
	v_pk_fma_f32 v[84:85], v[42:43], v[134:135], v[122:123] op_sel_hi:[1,0,1]
	v_pk_fma_f32 v[86:87], v[44:45], v[134:135], v[124:125] op_sel_hi:[1,0,1]
	v_pk_fma_f32 v[88:89], v[38:39], v[134:135], v[126:127] op_sel_hi:[1,0,1]
	v_pk_fma_f32 v[90:91], v[40:41], v[134:135], v[128:129] op_sel_hi:[1,0,1]
	s_waitcnt lgkmcnt(0)
	v_pk_mul_f32 v[114:115], v[34:35], v[74:75] op_sel_hi:[0,1]
	v_pk_mul_f32 v[116:117], v[34:35], v[78:79] op_sel_hi:[0,1]
	v_pk_fma_f32 v[106:107], v[114:115], v[2:3], 0 op_sel_hi:[1,1,0]
	v_pk_fma_f32 v[108:109], v[114:115], v[30:31], 0 op_sel_hi:[1,1,0]
	v_pk_mul_f32 v[118:119], v[34:35], v[80:81] op_sel_hi:[0,1]
	ds_read_b128 v[66:69], v94 offset:12000
	v_pk_fma_f32 v[106:107], v[116:117], v[4:5], v[106:107]
	v_pk_fma_f32 v[108:109], v[116:117], v[32:33], v[108:109]
	v_pk_mul_f32 v[120:121], v[34:35], v[82:83] op_sel_hi:[0,1]
	ds_read_b128 v[62:65], v94 offset:12016
	v_pk_fma_f32 v[106:107], v[118:119], v[6:7], v[106:107]
	v_pk_fma_f32 v[108:109], v[118:119], v[26:27], v[108:109]
	v_pk_mul_f32 v[122:123], v[34:35], v[84:85] op_sel_hi:[0,1]
	ds_read_b128 v[58:61], v94 offset:12032
	v_pk_fma_f32 v[106:107], v[120:121], v[8:9], v[106:107]
	v_pk_fma_f32 v[108:109], v[120:121], v[28:29], v[108:109]
	v_pk_mul_f32 v[124:125], v[34:35], v[86:87] op_sel_hi:[0,1]
	ds_read_b128 v[54:57], v94 offset:12048
	v_pk_fma_f32 v[106:107], v[122:123], v[14:15], v[106:107]
	v_pk_fma_f32 v[108:109], v[122:123], v[22:23], v[108:109]
	v_pk_mul_f32 v[126:127], v[34:35], v[88:89] op_sel_hi:[0,1]
	ds_read_b128 v[50:53], v94 offset:12256
	v_pk_fma_f32 v[106:107], v[124:125], v[16:17], v[106:107]
	v_pk_fma_f32 v[108:109], v[124:125], v[24:25], v[108:109]
	v_pk_mul_f32 v[128:129], v[34:35], v[90:91] op_sel_hi:[0,1]
	ds_read_b128 v[46:49], v94 offset:12272
	v_pk_fma_f32 v[106:107], v[126:127], v[10:11], v[106:107]
	v_pk_fma_f32 v[108:109], v[126:127], v[18:19], v[108:109]
	ds_read_b128 v[42:45], v94 offset:12288
	v_pk_fma_f32 v[106:107], v[128:129], v[12:13], v[106:107]
	v_pk_fma_f32 v[108:109], v[128:129], v[20:21], v[108:109]
	ds_read_b128 v[38:41], v94 offset:12304
	v_add_f32_e32 v130, v106, v107
	v_add_f32_e32 v131, v108, v109
	ds_read_b32 v0, v95 offset:12512
	v_add_f32_dpp v130, v130, v130 quad_perm:[1,0,3,2] row_mask:0xf bank_mask:0xf bound_ctrl:1
	v_add_f32_dpp v131, v131, v131 quad_perm:[1,0,3,2] row_mask:0xf bank_mask:0xf bound_ctrl:1
	ds_read_b96 v[70:72], v1 offset:12768
	v_add_f32_dpp v130, v130, v130 quad_perm:[2,3,0,1] row_mask:0xf bank_mask:0xf bound_ctrl:1
	v_add_f32_dpp v131, v131, v131 quad_perm:[2,3,0,1] row_mask:0xf bank_mask:0xf bound_ctrl:1
	v_sub_f32_e32 v130, v73, v130
	v_mul_f32_e32 v130, v35, v130
	v_fma_f32 v131, v36, v130, v131
	v_cvt_pk_bf16_f32 v132, v131, v131
	v_pk_fma_f32 v[74:75], v[2:3], v[130:131], v[114:115] op_sel_hi:[1,0,1]
	v_pk_fma_f32 v[78:79], v[4:5], v[130:131], v[116:117] op_sel_hi:[1,0,1]
	global_store_short v158, v132, s[100:101]
	v_pk_fma_f32 v[80:81], v[6:7], v[130:131], v[118:119] op_sel_hi:[1,0,1]
	v_pk_fma_f32 v[82:83], v[8:9], v[130:131], v[120:121] op_sel_hi:[1,0,1]
	v_pk_fma_f32 v[84:85], v[14:15], v[130:131], v[122:123] op_sel_hi:[1,0,1]
	v_pk_fma_f32 v[86:87], v[16:17], v[130:131], v[124:125] op_sel_hi:[1,0,1]
	v_pk_fma_f32 v[88:89], v[10:11], v[130:131], v[126:127] op_sel_hi:[1,0,1]
	v_pk_fma_f32 v[90:91], v[12:13], v[130:131], v[128:129] op_sel_hi:[1,0,1]
	s_waitcnt lgkmcnt(0)
	v_pk_mul_f32 v[114:115], v[70:71], v[74:75] op_sel_hi:[0,1]
	v_pk_mul_f32 v[116:117], v[70:71], v[78:79] op_sel_hi:[0,1]
	v_pk_fma_f32 v[110:111], v[114:115], v[50:51], 0 op_sel_hi:[1,1,0]
	v_pk_fma_f32 v[112:113], v[114:115], v[66:67], 0 op_sel_hi:[1,1,0]
	v_pk_mul_f32 v[118:119], v[70:71], v[80:81] op_sel_hi:[0,1]
	v_pk_fma_f32 v[110:111], v[116:117], v[52:53], v[110:111]
	v_pk_fma_f32 v[112:113], v[116:117], v[68:69], v[112:113]
	v_pk_mul_f32 v[120:121], v[70:71], v[82:83] op_sel_hi:[0,1]
	v_pk_fma_f32 v[110:111], v[118:119], v[46:47], v[110:111]
	v_pk_fma_f32 v[112:113], v[118:119], v[62:63], v[112:113]
	v_pk_mul_f32 v[122:123], v[70:71], v[84:85] op_sel_hi:[0,1]
	v_pk_fma_f32 v[110:111], v[120:121], v[48:49], v[110:111]
	v_pk_fma_f32 v[112:113], v[120:121], v[64:65], v[112:113]
	v_pk_mul_f32 v[124:125], v[70:71], v[86:87] op_sel_hi:[0,1]
	v_pk_fma_f32 v[110:111], v[122:123], v[42:43], v[110:111]
	v_pk_fma_f32 v[112:113], v[122:123], v[58:59], v[112:113]
	v_pk_mul_f32 v[126:127], v[70:71], v[88:89] op_sel_hi:[0,1]
	v_pk_fma_f32 v[110:111], v[124:125], v[44:45], v[110:111]
	v_pk_fma_f32 v[112:113], v[124:125], v[60:61], v[112:113]
	v_pk_mul_f32 v[128:129], v[70:71], v[90:91] op_sel_hi:[0,1]
	v_pk_fma_f32 v[110:111], v[126:127], v[38:39], v[110:111]
	v_pk_fma_f32 v[112:113], v[126:127], v[54:55], v[112:113]
	v_pk_fma_f32 v[110:111], v[128:129], v[40:41], v[110:111]
	v_pk_fma_f32 v[112:113], v[128:129], v[56:57], v[112:113]
	v_add_f32_e32 v134, v110, v111
	v_add_f32_e32 v135, v112, v113
	s_nop 0
	v_add_f32_dpp v134, v134, v134 quad_perm:[1,0,3,2] row_mask:0xf bank_mask:0xf bound_ctrl:1
	v_add_f32_dpp v135, v135, v135 quad_perm:[1,0,3,2] row_mask:0xf bank_mask:0xf bound_ctrl:1
	s_nop 0
	v_add_f32_dpp v134, v134, v134 quad_perm:[2,3,0,1] row_mask:0xf bank_mask:0xf bound_ctrl:1
	v_add_f32_dpp v135, v135, v135 quad_perm:[2,3,0,1] row_mask:0xf bank_mask:0xf bound_ctrl:1
	v_sub_f32_e32 v134, v0, v134
	v_mul_f32_e32 v134, v71, v134
	v_fma_f32 v135, v72, v134, v135
	v_cvt_pk_bf16_f32 v133, v135, v135
	v_pk_fma_f32 v[74:75], v[50:51], v[134:135], v[114:115] op_sel_hi:[1,0,1]
	v_pk_fma_f32 v[78:79], v[52:53], v[134:135], v[116:117] op_sel_hi:[1,0,1]
	global_store_short v159, v133, s[100:101]
	v_pk_fma_f32 v[80:81], v[46:47], v[134:135], v[118:119] op_sel_hi:[1,0,1]
	v_pk_fma_f32 v[82:83], v[48:49], v[134:135], v[120:121] op_sel_hi:[1,0,1]
	v_pk_fma_f32 v[84:85], v[42:43], v[134:135], v[122:123] op_sel_hi:[1,0,1]
	v_pk_fma_f32 v[86:87], v[44:45], v[134:135], v[124:125] op_sel_hi:[1,0,1]
	v_pk_fma_f32 v[88:89], v[38:39], v[134:135], v[126:127] op_sel_hi:[1,0,1]
	v_pk_fma_f32 v[90:91], v[40:41], v[134:135], v[128:129] op_sel_hi:[1,0,1]
.LBB0_910:
	s_waitcnt lgkmcnt(0)
	s_barrier
	ds_read_b128 v[30:33], v94 offset:12800
	ds_read_b128 v[26:29], v94 offset:12816
	ds_read_b128 v[22:25], v94 offset:12832
	ds_read_b128 v[18:21], v94 offset:12848
	ds_read_b128 v[2:5], v94 offset:13056
	ds_read_b128 v[6:9], v94 offset:13072
	ds_read_b32 v73, v95 offset:13312
	ds_read_b128 v[34:37], v1 offset:13568
	ds_read_b128 v[14:17], v94 offset:13088
	ds_read_b128 v[10:13], v94 offset:13104
	s_or_b32 s7, s6, 16
	s_mov_b64 s[18:19], -1
	s_and_b64 vcc, exec, s[16:17]
	s_cbranch_vccz .LBB0_912
	v_readlane_b32 s8, v254, 7
	s_sub_i32 s2, 0x8ff, s7
	s_addk_i32 s6, 0xff10
	v_readlane_b32 s9, v254, 8
	s_and_b64 s[10:11], s[8:9], exec
	s_cselect_b32 s2, s6, s2
	v_readlane_b32 s3, v254, 10
	s_add_i32 s16, s2, s3
	s_mov_b64 s[18:19], 0

.LBB0_916:
	s_nop 0
	v_readfirstlane_b32 s100, v92
	v_readfirstlane_b32 s101, v93
	s_sub_u32 s100, s100, m0
	s_subb_u32 s101, s101, 0
	s_waitcnt lgkmcnt(0)
	v_pk_mul_f32 v[114:115], v[34:35], v[74:75] op_sel_hi:[0,1]
	v_pk_mul_f32 v[116:117], v[34:35], v[78:79] op_sel_hi:[0,1]
	v_pk_fma_f32 v[106:107], v[114:115], v[2:3], 0 op_sel_hi:[1,1,0]
	v_pk_fma_f32 v[108:109], v[114:115], v[30:31], 0 op_sel_hi:[1,1,0]
	v_pk_mul_f32 v[118:119], v[34:35], v[80:81] op_sel_hi:[0,1]
	ds_read_b128 v[66:69], v94 offset:13600
	v_pk_fma_f32 v[106:107], v[116:117], v[4:5], v[106:107]
	v_pk_fma_f32 v[108:109], v[116:117], v[32:33], v[108:109]
	v_pk_mul_f32 v[120:121], v[34:35], v[82:83] op_sel_hi:[0,1]
	ds_read_b128 v[62:65], v94 offset:13616
	v_pk_fma_f32 v[106:107], v[118:119], v[6:7], v[106:107]
	v_pk_fma_f32 v[108:109], v[118:119], v[26:27], v[108:109]
	v_pk_mul_f32 v[122:123], v[34:35], v[84:85] op_sel_hi:[0,1]
	ds_read_b128 v[58:61], v94 offset:13632
	v_pk_fma_f32 v[106:107], v[120:121], v[8:9], v[106:107]
	v_pk_fma_f32 v[108:109], v[120:121], v[28:29], v[108:109]
	v_pk_mul_f32 v[124:125], v[34:35], v[86:87] op_sel_hi:[0,1]
	ds_read_b128 v[54:57], v94 offset:13648
	v_pk_fma_f32 v[106:107], v[122:123], v[14:15], v[106:107]
	v_pk_fma_f32 v[108:109], v[122:123], v[22:23], v[108:109]
	v_pk_mul_f32 v[126:127], v[34:35], v[88:89] op_sel_hi:[0,1]
	ds_read_b128 v[50:53], v94 offset:13856
	v_pk_fma_f32 v[106:107], v[124:125], v[16:17], v[106:107]
	v_pk_fma_f32 v[108:109], v[124:125], v[24:25], v[108:109]
	v_pk_mul_f32 v[128:129], v[34:35], v[90:91] op_sel_hi:[0,1]
	ds_read_b128 v[46:49], v94 offset:13872
	v_pk_fma_f32 v[106:107], v[126:127], v[10:11], v[106:107]
	v_pk_fma_f32 v[108:109], v[126:127], v[18:19], v[108:109]
	ds_read_b128 v[42:45], v94 offset:13888
	v_pk_fma_f32 v[106:107], v[128:129], v[12:13], v[106:107]
	v_pk_fma_f32 v[108:109], v[128:129], v[20:21], v[108:109]
	ds_read_b128 v[38:41], v94 offset:13904
	v_add_f32_e32 v130, v106, v107
	v_add_f32_e32 v131, v108, v109
	ds_read_b32 v0, v95 offset:14112
	v_add_f32_dpp v130, v130, v130 quad_perm:[1,0,3,2] row_mask:0xf bank_mask:0xf bound_ctrl:1
	v_add_f32_dpp v131, v131, v131 quad_perm:[1,0,3,2] row_mask:0xf bank_mask:0xf bound_ctrl:1
	ds_read_b96 v[70:72], v1 offset:14368
	v_add_f32_dpp v130, v130, v130 quad_perm:[2,3,0,1] row_mask:0xf bank_mask:0xf bound_ctrl:1
	v_add_f32_dpp v131, v131, v131 quad_perm:[2,3,0,1] row_mask:0xf bank_mask:0xf bound_ctrl:1
	v_sub_f32_e32 v130, v73, v130
	v_mul_f32_e32 v130, v35, v130
	v_fma_f32 v131, v36, v130, v131
	v_cvt_pk_bf16_f32 v132, v131, v131
	v_pk_fma_f32 v[74:75], v[2:3], v[130:131], v[114:115] op_sel_hi:[1,0,1]
	v_pk_fma_f32 v[78:79], v[4:5], v[130:131], v[116:117] op_sel_hi:[1,0,1]
	global_store_short v144, v132, s[100:101]
	v_pk_fma_f32 v[80:81], v[6:7], v[130:131], v[118:119] op_sel_hi:[1,0,1]
	v_pk_fma_f32 v[82:83], v[8:9], v[130:131], v[120:121] op_sel_hi:[1,0,1]
	v_pk_fma_f32 v[84:85], v[14:15], v[130:131], v[122:123] op_sel_hi:[1,0,1]
	v_pk_fma_f32 v[86:87], v[16:17], v[130:131], v[124:125] op_sel_hi:[1,0,1]
	v_pk_fma_f32 v[88:89], v[10:11], v[130:131], v[126:127] op_sel_hi:[1,0,1]
	v_pk_fma_f32 v[90:91], v[12:13], v[130:131], v[128:129] op_sel_hi:[1,0,1]
	s_waitcnt lgkmcnt(0)
	v_pk_mul_f32 v[114:115], v[70:71], v[74:75] op_sel_hi:[0,1]
	v_pk_mul_f32 v[116:117], v[70:71], v[78:79] op_sel_hi:[0,1]
	v_pk_fma_f32 v[110:111], v[114:115], v[50:51], 0 op_sel_hi:[1,1,0]
	v_pk_fma_f32 v[112:113], v[114:115], v[66:67], 0 op_sel_hi:[1,1,0]
	v_pk_mul_f32 v[118:119], v[70:71], v[80:81] op_sel_hi:[0,1]
	ds_read_b128 v[30:33], v94 offset:14400
	v_pk_fma_f32 v[110:111], v[116:117], v[52:53], v[110:111]
	v_pk_fma_f32 v[112:113], v[116:117], v[68:69], v[112:113]
	v_pk_mul_f32 v[120:121], v[70:71], v[82:83] op_sel_hi:[0,1]
	ds_read_b128 v[26:29], v94 offset:14416
	v_pk_fma_f32 v[110:111], v[118:119], v[46:47], v[110:111]
	v_pk_fma_f32 v[112:113], v[118:119], v[62:63], v[112:113]
	v_pk_mul_f32 v[122:123], v[70:71], v[84:85] op_sel_hi:[0,1]
	ds_read_b128 v[22:25], v94 offset:14432
	v_pk_fma_f32 v[110:111], v[120:121], v[48:49], v[110:111]
	v_pk_fma_f32 v[112:113], v[120:121], v[64:65], v[112:113]
	v_pk_mul_f32 v[124:125], v[70:71], v[86:87] op_sel_hi:[0,1]
	ds_read_b128 v[18:21], v94 offset:14448
	v_pk_fma_f32 v[110:111], v[122:123], v[42:43], v[110:111]
	v_pk_fma_f32 v[112:113], v[122:123], v[58:59], v[112:113]
	v_pk_mul_f32 v[126:127], v[70:71], v[88:89] op_sel_hi:[0,1]
	ds_read_b128 v[2:5], v94 offset:14656
	v_pk_fma_f32 v[110:111], v[124:125], v[44:45], v[110:111]
	v_pk_fma_f32 v[112:113], v[124:125], v[60:61], v[112:113]
	v_pk_mul_f32 v[128:129], v[70:71], v[90:91] op_sel_hi:[0,1]
	ds_read_b128 v[6:9], v94 offset:14672
	v_pk_fma_f32 v[110:111], v[126:127], v[38:39], v[110:111]
	v_pk_fma_f32 v[112:113], v[126:127], v[54:55], v[112:113]
	ds_read_b128 v[14:17], v94 offset:14688
	v_pk_fma_f32 v[110:111], v[128:129], v[40:41], v[110:111]
	v_pk_fma_f32 v[112:113], v[128:129], v[56:57], v[112:113]
	ds_read_b128 v[10:13], v94 offset:14704
	v_add_f32_e32 v134, v110, v111
	v_add_f32_e32 v135, v112, v113
	ds_read_b32 v73, v95 offset:14912
	v_add_f32_dpp v134, v134, v134 quad_perm:[1,0,3,2] row_mask:0xf bank_mask:0xf bound_ctrl:1
	v_add_f32_dpp v135, v135, v135 quad_perm:[1,0,3,2] row_mask:0xf bank_mask:0xf bound_ctrl:1
	ds_read_b96 v[34:36], v1 offset:15168
	v_add_f32_dpp v134, v134, v134 quad_perm:[2,3,0,1] row_mask:0xf bank_mask:0xf bound_ctrl:1
	v_add_f32_dpp v135, v135, v135 quad_perm:[2,3,0,1] row_mask:0xf bank_mask:0xf bound_ctrl:1
	v_sub_f32_e32 v134, v0, v134
	v_mul_f32_e32 v134, v71, v134
	v_fma_f32 v135, v72, v134, v135
	v_cvt_pk_bf16_f32 v133, v135, v135
	v_pk_fma_f32 v[74:75], v[50:51], v[134:135], v[114:115] op_sel_hi:[1,0,1]
	v_pk_fma_f32 v[78:79], v[52:53], v[134:135], v[116:117] op_sel_hi:[1,0,1]
	global_store_short v145, v133, s[100:101]
	v_pk_fma_f32 v[80:81], v[46:47], v[134:135], v[118:119] op_sel_hi:[1,0,1]
	v_pk_fma_f32 v[82:83], v[48:49], v[134:135], v[120:121] op_sel_hi:[1,0,1]
	v_pk_fma_f32 v[84:85], v[42:43], v[134:135], v[122:123] op_sel_hi:[1,0,1]
	v_pk_fma_f32 v[86:87], v[44:45], v[134:135], v[124:125] op_sel_hi:[1,0,1]
	v_pk_fma_f32 v[88:89], v[38:39], v[134:135], v[126:127] op_sel_hi:[1,0,1]
	v_pk_fma_f32 v[90:91], v[40:41], v[134:135], v[128:129] op_sel_hi:[1,0,1]
	s_waitcnt lgkmcnt(0)
	v_pk_mul_f32 v[114:115], v[34:35], v[74:75] op_sel_hi:[0,1]
	v_pk_mul_f32 v[116:117], v[34:35], v[78:79] op_sel_hi:[0,1]
	v_pk_fma_f32 v[106:107], v[114:115], v[2:3], 0 op_sel_hi:[1,1,0]
	v_pk_fma_f32 v[108:109], v[114:115], v[30:31], 0 op_sel_hi:[1,1,0]
	v_pk_mul_f32 v[118:119], v[34:35], v[80:81] op_sel_hi:[0,1]
	ds_read_b128 v[66:69], v94 offset:15200
	v_pk_fma_f32 v[106:107], v[116:117], v[4:5], v[106:107]
	v_pk_fma_f32 v[108:109], v[116:117], v[32:33], v[108:109]
	v_pk_mul_f32 v[120:121], v[34:35], v[82:83] op_sel_hi:[0,1]
	ds_read_b128 v[62:65], v94 offset:15216
	v_pk_fma_f32 v[106:107], v[118:119], v[6:7], v[106:107]
	v_pk_fma_f32 v[108:109], v[118:119], v[26:27], v[108:109]
	v_pk_mul_f32 v[122:123], v[34:35], v[84:85] op_sel_hi:[0,1]
	ds_read_b128 v[58:61], v94 offset:15232
	v_pk_fma_f32 v[106:107], v[120:121], v[8:9], v[106:107]
	v_pk_fma_f32 v[108:109], v[120:121], v[28:29], v[108:109]
	v_pk_mul_f32 v[124:125], v[34:35], v[86:87] op_sel_hi:[0,1]
	ds_read_b128 v[54:57], v94 offset:15248
	v_pk_fma_f32 v[106:107], v[122:123], v[14:15], v[106:107]
	v_pk_fma_f32 v[108:109], v[122:123], v[22:23], v[108:109]
	v_pk_mul_f32 v[126:127], v[34:35], v[88:89] op_sel_hi:[0,1]
	ds_read_b128 v[50:53], v94 offset:15456
	v_pk_fma_f32 v[106:107], v[124:125], v[16:17], v[106:107]
	v_pk_fma_f32 v[108:109], v[124:125], v[24:25], v[108:109]
	v_pk_mul_f32 v[128:129], v[34:35], v[90:91] op_sel_hi:[0,1]
	ds_read_b128 v[46:49], v94 offset:15472
	v_pk_fma_f32 v[106:107], v[126:127], v[10:11], v[106:107]
	v_pk_fma_f32 v[108:109], v[126:127], v[18:19], v[108:109]
	ds_read_b128 v[42:45], v94 offset:15488
	v_pk_fma_f32 v[106:107], v[128:129], v[12:13], v[106:107]
	v_pk_fma_f32 v[108:109], v[128:129], v[20:21], v[108:109]
	ds_read_b128 v[38:41], v94 offset:15504
	v_add_f32_e32 v130, v106, v107
	v_add_f32_e32 v131, v108, v109
	ds_read_b32 v0, v95 offset:15712
	v_add_f32_dpp v130, v130, v130 quad_perm:[1,0,3,2] row_mask:0xf bank_mask:0xf bound_ctrl:1
	v_add_f32_dpp v131, v131, v131 quad_perm:[1,0,3,2] row_mask:0xf bank_mask:0xf bound_ctrl:1
	ds_read_b96 v[70:72], v1 offset:15968
	v_add_f32_dpp v130, v130, v130 quad_perm:[2,3,0,1] row_mask:0xf bank_mask:0xf bound_ctrl:1
	v_add_f32_dpp v131, v131, v131 quad_perm:[2,3,0,1] row_mask:0xf bank_mask:0xf bound_ctrl:1
	v_sub_f32_e32 v130, v73, v130
	v_mul_f32_e32 v130, v35, v130
	v_fma_f32 v131, v36, v130, v131
	v_cvt_pk_bf16_f32 v132, v131, v131
	v_pk_fma_f32 v[74:75], v[2:3], v[130:131], v[114:115] op_sel_hi:[1,0,1]
	v_pk_fma_f32 v[78:79], v[4:5], v[130:131], v[116:117] op_sel_hi:[1,0,1]
	global_store_short v146, v132, s[100:101]
	v_pk_fma_f32 v[80:81], v[6:7], v[130:131], v[118:119] op_sel_hi:[1,0,1]
	v_pk_fma_f32 v[82:83], v[8:9], v[130:131], v[120:121] op_sel_hi:[1,0,1]
	v_pk_fma_f32 v[84:85], v[14:15], v[130:131], v[122:123] op_sel_hi:[1,0,1]
	v_pk_fma_f32 v[86:87], v[16:17], v[130:131], v[124:125] op_sel_hi:[1,0,1]
	v_pk_fma_f32 v[88:89], v[10:11], v[130:131], v[126:127] op_sel_hi:[1,0,1]
	v_pk_fma_f32 v[90:91], v[12:13], v[130:131], v[128:129] op_sel_hi:[1,0,1]
	s_waitcnt lgkmcnt(0)
	v_pk_mul_f32 v[114:115], v[70:71], v[74:75] op_sel_hi:[0,1]
	v_pk_mul_f32 v[116:117], v[70:71], v[78:79] op_sel_hi:[0,1]
	v_pk_fma_f32 v[110:111], v[114:115], v[50:51], 0 op_sel_hi:[1,1,0]
	v_pk_fma_f32 v[112:113], v[114:115], v[66:67], 0 op_sel_hi:[1,1,0]
	v_pk_mul_f32 v[118:119], v[70:71], v[80:81] op_sel_hi:[0,1]
	ds_read_b128 v[30:33], v94 offset:16000
	v_pk_fma_f32 v[110:111], v[116:117], v[52:53], v[110:111]
	v_pk_fma_f32 v[112:113], v[116:117], v[68:69], v[112:113]
	v_pk_mul_f32 v[120:121], v[70:71], v[82:83] op_sel_hi:[0,1]
	ds_read_b128 v[26:29], v94 offset:16016
	v_pk_fma_f32 v[110:111], v[118:119], v[46:47], v[110:111]
	v_pk_fma_f32 v[112:113], v[118:119], v[62:63], v[112:113]
	v_pk_mul_f32 v[122:123], v[70:71], v[84:85] op_sel_hi:[0,1]
	ds_read_b128 v[22:25], v94 offset:16032
	v_pk_fma_f32 v[110:111], v[120:121], v[48:49], v[110:111]
	v_pk_fma_f32 v[112:113], v[120:121], v[64:65], v[112:113]
	v_pk_mul_f32 v[124:125], v[70:71], v[86:87] op_sel_hi:[0,1]
	ds_read_b128 v[18:21], v94 offset:16048
	v_pk_fma_f32 v[110:111], v[122:123], v[42:43], v[110:111]
	v_pk_fma_f32 v[112:113], v[122:123], v[58:59], v[112:113]
	v_pk_mul_f32 v[126:127], v[70:71], v[88:89] op_sel_hi:[0,1]
	ds_read_b128 v[2:5], v94 offset:16256
	v_pk_fma_f32 v[110:111], v[124:125], v[44:45], v[110:111]
	v_pk_fma_f32 v[112:113], v[124:125], v[60:61], v[112:113]
	v_pk_mul_f32 v[128:129], v[70:71], v[90:91] op_sel_hi:[0,1]
	ds_read_b128 v[6:9], v94 offset:16272
	v_pk_fma_f32 v[110:111], v[126:127], v[38:39], v[110:111]
	v_pk_fma_f32 v[112:113], v[126:127], v[54:55], v[112:113]
	ds_read_b128 v[14:17], v94 offset:16288
	v_pk_fma_f32 v[110:111], v[128:129], v[40:41], v[110:111]
	v_pk_fma_f32 v[112:113], v[128:129], v[56:57], v[112:113]
	ds_read_b128 v[10:13], v94 offset:16304
	v_add_f32_e32 v134, v110, v111
	v_add_f32_e32 v135, v112, v113
	ds_read_b32 v73, v95 offset:16512
	v_add_f32_dpp v134, v134, v134 quad_perm:[1,0,3,2] row_mask:0xf bank_mask:0xf bound_ctrl:1
	v_add_f32_dpp v135, v135, v135 quad_perm:[1,0,3,2] row_mask:0xf bank_mask:0xf bound_ctrl:1
	ds_read_b96 v[34:36], v1 offset:16768
	v_add_f32_dpp v134, v134, v134 quad_perm:[2,3,0,1] row_mask:0xf bank_mask:0xf bound_ctrl:1
	v_add_f32_dpp v135, v135, v135 quad_perm:[2,3,0,1] row_mask:0xf bank_mask:0xf bound_ctrl:1
	v_sub_f32_e32 v134, v0, v134
	v_mul_f32_e32 v134, v71, v134
	v_fma_f32 v135, v72, v134, v135
	v_cvt_pk_bf16_f32 v133, v135, v135
	v_pk_fma_f32 v[74:75], v[50:51], v[134:135], v[114:115] op_sel_hi:[1,0,1]
	v_pk_fma_f32 v[78:79], v[52:53], v[134:135], v[116:117] op_sel_hi:[1,0,1]
	global_store_short v147, v133, s[100:101]
	v_pk_fma_f32 v[80:81], v[46:47], v[134:135], v[118:119] op_sel_hi:[1,0,1]
	v_pk_fma_f32 v[82:83], v[48:49], v[134:135], v[120:121] op_sel_hi:[1,0,1]
	v_pk_fma_f32 v[84:85], v[42:43], v[134:135], v[122:123] op_sel_hi:[1,0,1]
	v_pk_fma_f32 v[86:87], v[44:45], v[134:135], v[124:125] op_sel_hi:[1,0,1]
	v_pk_fma_f32 v[88:89], v[38:39], v[134:135], v[126:127] op_sel_hi:[1,0,1]
	v_pk_fma_f32 v[90:91], v[40:41], v[134:135], v[128:129] op_sel_hi:[1,0,1]
	s_waitcnt lgkmcnt(0)
	v_pk_mul_f32 v[114:115], v[34:35], v[74:75] op_sel_hi:[0,1]
	v_pk_mul_f32 v[116:117], v[34:35], v[78:79] op_sel_hi:[0,1]
	v_pk_fma_f32 v[106:107], v[114:115], v[2:3], 0 op_sel_hi:[1,1,0]
	v_pk_fma_f32 v[108:109], v[114:115], v[30:31], 0 op_sel_hi:[1,1,0]
	v_pk_mul_f32 v[118:119], v[34:35], v[80:81] op_sel_hi:[0,1]
	ds_read_b128 v[66:69], v94 offset:16800
	v_pk_fma_f32 v[106:107], v[116:117], v[4:5], v[106:107]
	v_pk_fma_f32 v[108:109], v[116:117], v[32:33], v[108:109]
	v_pk_mul_f32 v[120:121], v[34:35], v[82:83] op_sel_hi:[0,1]
	ds_read_b128 v[62:65], v94 offset:16816
	v_pk_fma_f32 v[106:107], v[118:119], v[6:7], v[106:107]
	v_pk_fma_f32 v[108:109], v[118:119], v[26:27], v[108:109]
	v_pk_mul_f32 v[122:123], v[34:35], v[84:85] op_sel_hi:[0,1]
	ds_read_b128 v[58:61], v94 offset:16832
	v_pk_fma_f32 v[106:107], v[120:121], v[8:9], v[106:107]
	v_pk_fma_f32 v[108:109], v[120:121], v[28:29], v[108:109]
	v_pk_mul_f32 v[124:125], v[34:35], v[86:87] op_sel_hi:[0,1]
	ds_read_b128 v[54:57], v94 offset:16848
	v_pk_fma_f32 v[106:107], v[122:123], v[14:15], v[106:107]
	v_pk_fma_f32 v[108:109], v[122:123], v[22:23], v[108:109]
	v_pk_mul_f32 v[126:127], v[34:35], v[88:89] op_sel_hi:[0,1]
	ds_read_b128 v[50:53], v94 offset:17056
	v_pk_fma_f32 v[106:107], v[124:125], v[16:17], v[106:107]
	v_pk_fma_f32 v[108:109], v[124:125], v[24:25], v[108:109]
	v_pk_mul_f32 v[128:129], v[34:35], v[90:91] op_sel_hi:[0,1]
	ds_read_b128 v[46:49], v94 offset:17072
	v_pk_fma_f32 v[106:107], v[126:127], v[10:11], v[106:107]
	v_pk_fma_f32 v[108:109], v[126:127], v[18:19], v[108:109]
	ds_read_b128 v[42:45], v94 offset:17088
	v_pk_fma_f32 v[106:107], v[128:129], v[12:13], v[106:107]
	v_pk_fma_f32 v[108:109], v[128:129], v[20:21], v[108:109]
	ds_read_b128 v[38:41], v94 offset:17104
	v_add_f32_e32 v130, v106, v107
	v_add_f32_e32 v131, v108, v109
	ds_read_b32 v0, v95 offset:17312
	v_add_f32_dpp v130, v130, v130 quad_perm:[1,0,3,2] row_mask:0xf bank_mask:0xf bound_ctrl:1
	v_add_f32_dpp v131, v131, v131 quad_perm:[1,0,3,2] row_mask:0xf bank_mask:0xf bound_ctrl:1
	ds_read_b96 v[70:72], v1 offset:17568
	v_add_f32_dpp v130, v130, v130 quad_perm:[2,3,0,1] row_mask:0xf bank_mask:0xf bound_ctrl:1
	v_add_f32_dpp v131, v131, v131 quad_perm:[2,3,0,1] row_mask:0xf bank_mask:0xf bound_ctrl:1
	v_sub_f32_e32 v130, v73, v130
	v_mul_f32_e32 v130, v35, v130
	v_fma_f32 v131, v36, v130, v131
	v_cvt_pk_bf16_f32 v132, v131, v131
	v_pk_fma_f32 v[74:75], v[2:3], v[130:131], v[114:115] op_sel_hi:[1,0,1]
	v_pk_fma_f32 v[78:79], v[4:5], v[130:131], v[116:117] op_sel_hi:[1,0,1]
	global_store_short v148, v132, s[100:101]
	v_pk_fma_f32 v[80:81], v[6:7], v[130:131], v[118:119] op_sel_hi:[1,0,1]
	v_pk_fma_f32 v[82:83], v[8:9], v[130:131], v[120:121] op_sel_hi:[1,0,1]
	v_pk_fma_f32 v[84:85], v[14:15], v[130:131], v[122:123] op_sel_hi:[1,0,1]
	v_pk_fma_f32 v[86:87], v[16:17], v[130:131], v[124:125] op_sel_hi:[1,0,1]
	v_pk_fma_f32 v[88:89], v[10:11], v[130:131], v[126:127] op_sel_hi:[1,0,1]
	v_pk_fma_f32 v[90:91], v[12:13], v[130:131], v[128:129] op_sel_hi:[1,0,1]
	s_waitcnt lgkmcnt(0)
	v_pk_mul_f32 v[114:115], v[70:71], v[74:75] op_sel_hi:[0,1]
	v_pk_mul_f32 v[116:117], v[70:71], v[78:79] op_sel_hi:[0,1]
	v_pk_fma_f32 v[110:111], v[114:115], v[50:51], 0 op_sel_hi:[1,1,0]
	v_pk_fma_f32 v[112:113], v[114:115], v[66:67], 0 op_sel_hi:[1,1,0]
	v_pk_mul_f32 v[118:119], v[70:71], v[80:81] op_sel_hi:[0,1]
	ds_read_b128 v[30:33], v94 offset:17600
	v_pk_fma_f32 v[110:111], v[116:117], v[52:53], v[110:111]
	v_pk_fma_f32 v[112:113], v[116:117], v[68:69], v[112:113]
	v_pk_mul_f32 v[120:121], v[70:71], v[82:83] op_sel_hi:[0,1]
	ds_read_b128 v[26:29], v94 offset:17616
	v_pk_fma_f32 v[110:111], v[118:119], v[46:47], v[110:111]
	v_pk_fma_f32 v[112:113], v[118:119], v[62:63], v[112:113]
	v_pk_mul_f32 v[122:123], v[70:71], v[84:85] op_sel_hi:[0,1]
	ds_read_b128 v[22:25], v94 offset:17632
	v_pk_fma_f32 v[110:111], v[120:121], v[48:49], v[110:111]
	v_pk_fma_f32 v[112:113], v[120:121], v[64:65], v[112:113]
	v_pk_mul_f32 v[124:125], v[70:71], v[86:87] op_sel_hi:[0,1]
	ds_read_b128 v[18:21], v94 offset:17648
	v_pk_fma_f32 v[110:111], v[122:123], v[42:43], v[110:111]
	v_pk_fma_f32 v[112:113], v[122:123], v[58:59], v[112:113]
	v_pk_mul_f32 v[126:127], v[70:71], v[88:89] op_sel_hi:[0,1]
	ds_read_b128 v[2:5], v94 offset:17856
	v_pk_fma_f32 v[110:111], v[124:125], v[44:45], v[110:111]
	v_pk_fma_f32 v[112:113], v[124:125], v[60:61], v[112:113]
	v_pk_mul_f32 v[128:129], v[70:71], v[90:91] op_sel_hi:[0,1]
	ds_read_b128 v[6:9], v94 offset:17872
	v_pk_fma_f32 v[110:111], v[126:127], v[38:39], v[110:111]
	v_pk_fma_f32 v[112:113], v[126:127], v[54:55], v[112:113]
	ds_read_b128 v[14:17], v94 offset:17888
	v_pk_fma_f32 v[110:111], v[128:129], v[40:41], v[110:111]
	v_pk_fma_f32 v[112:113], v[128:129], v[56:57], v[112:113]
	ds_read_b128 v[10:13], v94 offset:17904
	v_add_f32_e32 v134, v110, v111
	v_add_f32_e32 v135, v112, v113
	ds_read_b32 v73, v95 offset:18112
	v_add_f32_dpp v134, v134, v134 quad_perm:[1,0,3,2] row_mask:0xf bank_mask:0xf bound_ctrl:1
	v_add_f32_dpp v135, v135, v135 quad_perm:[1,0,3,2] row_mask:0xf bank_mask:0xf bound_ctrl:1
	ds_read_b96 v[34:36], v1 offset:18368
	v_add_f32_dpp v134, v134, v134 quad_perm:[2,3,0,1] row_mask:0xf bank_mask:0xf bound_ctrl:1
	v_add_f32_dpp v135, v135, v135 quad_perm:[2,3,0,1] row_mask:0xf bank_mask:0xf bound_ctrl:1
	v_sub_f32_e32 v134, v0, v134
	v_mul_f32_e32 v134, v71, v134
	v_fma_f32 v135, v72, v134, v135
	v_cvt_pk_bf16_f32 v133, v135, v135
	v_pk_fma_f32 v[74:75], v[50:51], v[134:135], v[114:115] op_sel_hi:[1,0,1]
	v_pk_fma_f32 v[78:79], v[52:53], v[134:135], v[116:117] op_sel_hi:[1,0,1]
	global_store_short v149, v133, s[100:101]
	v_pk_fma_f32 v[80:81], v[46:47], v[134:135], v[118:119] op_sel_hi:[1,0,1]
	v_pk_fma_f32 v[82:83], v[48:49], v[134:135], v[120:121] op_sel_hi:[1,0,1]
	v_pk_fma_f32 v[84:85], v[42:43], v[134:135], v[122:123] op_sel_hi:[1,0,1]
	v_pk_fma_f32 v[86:87], v[44:45], v[134:135], v[124:125] op_sel_hi:[1,0,1]
	v_pk_fma_f32 v[88:89], v[38:39], v[134:135], v[126:127] op_sel_hi:[1,0,1]
	v_pk_fma_f32 v[90:91], v[40:41], v[134:135], v[128:129] op_sel_hi:[1,0,1]
	s_waitcnt lgkmcnt(0)
	v_pk_mul_f32 v[114:115], v[34:35], v[74:75] op_sel_hi:[0,1]
	v_pk_mul_f32 v[116:117], v[34:35], v[78:79] op_sel_hi:[0,1]
	v_pk_fma_f32 v[106:107], v[114:115], v[2:3], 0 op_sel_hi:[1,1,0]
	v_pk_fma_f32 v[108:109], v[114:115], v[30:31], 0 op_sel_hi:[1,1,0]
	v_pk_mul_f32 v[118:119], v[34:35], v[80:81] op_sel_hi:[0,1]
	ds_read_b128 v[66:69], v94 offset:18400
	v_pk_fma_f32 v[106:107], v[116:117], v[4:5], v[106:107]
	v_pk_fma_f32 v[108:109], v[116:117], v[32:33], v[108:109]
	v_pk_mul_f32 v[120:121], v[34:35], v[82:83] op_sel_hi:[0,1]
	ds_read_b128 v[62:65], v94 offset:18416
	v_pk_fma_f32 v[106:107], v[118:119], v[6:7], v[106:107]
	v_pk_fma_f32 v[108:109], v[118:119], v[26:27], v[108:109]
	v_pk_mul_f32 v[122:123], v[34:35], v[84:85] op_sel_hi:[0,1]
	ds_read_b128 v[58:61], v94 offset:18432
	v_pk_fma_f32 v[106:107], v[120:121], v[8:9], v[106:107]
	v_pk_fma_f32 v[108:109], v[120:121], v[28:29], v[108:109]
	v_pk_mul_f32 v[124:125], v[34:35], v[86:87] op_sel_hi:[0,1]
	ds_read_b128 v[54:57], v94 offset:18448
	v_pk_fma_f32 v[106:107], v[122:123], v[14:15], v[106:107]
	v_pk_fma_f32 v[108:109], v[122:123], v[22:23], v[108:109]
	v_pk_mul_f32 v[126:127], v[34:35], v[88:89] op_sel_hi:[0,1]
	ds_read_b128 v[50:53], v94 offset:18656
	v_pk_fma_f32 v[106:107], v[124:125], v[16:17], v[106:107]
	v_pk_fma_f32 v[108:109], v[124:125], v[24:25], v[108:109]
	v_pk_mul_f32 v[128:129], v[34:35], v[90:91] op_sel_hi:[0,1]
	ds_read_b128 v[46:49], v94 offset:18672
	v_pk_fma_f32 v[106:107], v[126:127], v[10:11], v[106:107]
	v_pk_fma_f32 v[108:109], v[126:127], v[18:19], v[108:109]
	ds_read_b128 v[42:45], v94 offset:18688
	v_pk_fma_f32 v[106:107], v[128:129], v[12:13], v[106:107]
	v_pk_fma_f32 v[108:109], v[128:129], v[20:21], v[108:109]
	ds_read_b128 v[38:41], v94 offset:18704
	v_add_f32_e32 v130, v106, v107
	v_add_f32_e32 v131, v108, v109
	ds_read_b32 v0, v95 offset:18912
	v_add_f32_dpp v130, v130, v130 quad_perm:[1,0,3,2] row_mask:0xf bank_mask:0xf bound_ctrl:1
	v_add_f32_dpp v131, v131, v131 quad_perm:[1,0,3,2] row_mask:0xf bank_mask:0xf bound_ctrl:1
	ds_read_b96 v[70:72], v1 offset:19168
	v_add_f32_dpp v130, v130, v130 quad_perm:[2,3,0,1] row_mask:0xf bank_mask:0xf bound_ctrl:1
	v_add_f32_dpp v131, v131, v131 quad_perm:[2,3,0,1] row_mask:0xf bank_mask:0xf bound_ctrl:1
	v_sub_f32_e32 v130, v73, v130
	v_mul_f32_e32 v130, v35, v130
	v_fma_f32 v131, v36, v130, v131
	v_cvt_pk_bf16_f32 v132, v131, v131
	v_pk_fma_f32 v[74:75], v[2:3], v[130:131], v[114:115] op_sel_hi:[1,0,1]
	v_pk_fma_f32 v[78:79], v[4:5], v[130:131], v[116:117] op_sel_hi:[1,0,1]
	global_store_short v150, v132, s[100:101]
	v_pk_fma_f32 v[80:81], v[6:7], v[130:131], v[118:119] op_sel_hi:[1,0,1]
	v_pk_fma_f32 v[82:83], v[8:9], v[130:131], v[120:121] op_sel_hi:[1,0,1]
	v_pk_fma_f32 v[84:85], v[14:15], v[130:131], v[122:123] op_sel_hi:[1,0,1]
	v_pk_fma_f32 v[86:87], v[16:17], v[130:131], v[124:125] op_sel_hi:[1,0,1]
	v_pk_fma_f32 v[88:89], v[10:11], v[130:131], v[126:127] op_sel_hi:[1,0,1]
	v_pk_fma_f32 v[90:91], v[12:13], v[130:131], v[128:129] op_sel_hi:[1,0,1]
	s_waitcnt lgkmcnt(0)
	v_pk_mul_f32 v[114:115], v[70:71], v[74:75] op_sel_hi:[0,1]
	v_pk_mul_f32 v[116:117], v[70:71], v[78:79] op_sel_hi:[0,1]
	v_pk_fma_f32 v[110:111], v[114:115], v[50:51], 0 op_sel_hi:[1,1,0]
	v_pk_fma_f32 v[112:113], v[114:115], v[66:67], 0 op_sel_hi:[1,1,0]
	v_pk_mul_f32 v[118:119], v[70:71], v[80:81] op_sel_hi:[0,1]
	ds_read_b128 v[30:33], v94 offset:19200
	v_pk_fma_f32 v[110:111], v[116:117], v[52:53], v[110:111]
	v_pk_fma_f32 v[112:113], v[116:117], v[68:69], v[112:113]
	v_pk_mul_f32 v[120:121], v[70:71], v[82:83] op_sel_hi:[0,1]
	ds_read_b128 v[26:29], v94 offset:19216
	v_pk_fma_f32 v[110:111], v[118:119], v[46:47], v[110:111]
	v_pk_fma_f32 v[112:113], v[118:119], v[62:63], v[112:113]
	v_pk_mul_f32 v[122:123], v[70:71], v[84:85] op_sel_hi:[0,1]
	ds_read_b128 v[22:25], v94 offset:19232
	v_pk_fma_f32 v[110:111], v[120:121], v[48:49], v[110:111]
	v_pk_fma_f32 v[112:113], v[120:121], v[64:65], v[112:113]
	v_pk_mul_f32 v[124:125], v[70:71], v[86:87] op_sel_hi:[0,1]
	ds_read_b128 v[18:21], v94 offset:19248
	v_pk_fma_f32 v[110:111], v[122:123], v[42:43], v[110:111]
	v_pk_fma_f32 v[112:113], v[122:123], v[58:59], v[112:113]
	v_pk_mul_f32 v[126:127], v[70:71], v[88:89] op_sel_hi:[0,1]
	ds_read_b128 v[2:5], v94 offset:19456
	v_pk_fma_f32 v[110:111], v[124:125], v[44:45], v[110:111]
	v_pk_fma_f32 v[112:113], v[124:125], v[60:61], v[112:113]
	v_pk_mul_f32 v[128:129], v[70:71], v[90:91] op_sel_hi:[0,1]
	ds_read_b128 v[6:9], v94 offset:19472
	v_pk_fma_f32 v[110:111], v[126:127], v[38:39], v[110:111]
	v_pk_fma_f32 v[112:113], v[126:127], v[54:55], v[112:113]
	ds_read_b128 v[14:17], v94 offset:19488
	v_pk_fma_f32 v[110:111], v[128:129], v[40:41], v[110:111]
	v_pk_fma_f32 v[112:113], v[128:129], v[56:57], v[112:113]
	ds_read_b128 v[10:13], v94 offset:19504
	v_add_f32_e32 v134, v110, v111
	v_add_f32_e32 v135, v112, v113
	ds_read_b32 v73, v95 offset:19712
	v_add_f32_dpp v134, v134, v134 quad_perm:[1,0,3,2] row_mask:0xf bank_mask:0xf bound_ctrl:1
	v_add_f32_dpp v135, v135, v135 quad_perm:[1,0,3,2] row_mask:0xf bank_mask:0xf bound_ctrl:1
	ds_read_b96 v[34:36], v1 offset:19968
	v_add_f32_dpp v134, v134, v134 quad_perm:[2,3,0,1] row_mask:0xf bank_mask:0xf bound_ctrl:1
	v_add_f32_dpp v135, v135, v135 quad_perm:[2,3,0,1] row_mask:0xf bank_mask:0xf bound_ctrl:1
	v_sub_f32_e32 v134, v0, v134
	v_mul_f32_e32 v134, v71, v134
	v_fma_f32 v135, v72, v134, v135
	v_cvt_pk_bf16_f32 v133, v135, v135
	v_pk_fma_f32 v[74:75], v[50:51], v[134:135], v[114:115] op_sel_hi:[1,0,1]
	v_pk_fma_f32 v[78:79], v[52:53], v[134:135], v[116:117] op_sel_hi:[1,0,1]
	global_store_short v151, v133, s[100:101]
	v_pk_fma_f32 v[80:81], v[46:47], v[134:135], v[118:119] op_sel_hi:[1,0,1]
	v_pk_fma_f32 v[82:83], v[48:49], v[134:135], v[120:121] op_sel_hi:[1,0,1]
	v_pk_fma_f32 v[84:85], v[42:43], v[134:135], v[122:123] op_sel_hi:[1,0,1]
	v_pk_fma_f32 v[86:87], v[44:45], v[134:135], v[124:125] op_sel_hi:[1,0,1]
	v_pk_fma_f32 v[88:89], v[38:39], v[134:135], v[126:127] op_sel_hi:[1,0,1]
	v_pk_fma_f32 v[90:91], v[40:41], v[134:135], v[128:129] op_sel_hi:[1,0,1]
	s_waitcnt lgkmcnt(0)
	v_pk_mul_f32 v[114:115], v[34:35], v[74:75] op_sel_hi:[0,1]
	v_pk_mul_f32 v[116:117], v[34:35], v[78:79] op_sel_hi:[0,1]
	v_pk_fma_f32 v[106:107], v[114:115], v[2:3], 0 op_sel_hi:[1,1,0]
	v_pk_fma_f32 v[108:109], v[114:115], v[30:31], 0 op_sel_hi:[1,1,0]
	v_pk_mul_f32 v[118:119], v[34:35], v[80:81] op_sel_hi:[0,1]
	ds_read_b128 v[66:69], v94 offset:20000
	v_pk_fma_f32 v[106:107], v[116:117], v[4:5], v[106:107]
	v_pk_fma_f32 v[108:109], v[116:117], v[32:33], v[108:109]
	v_pk_mul_f32 v[120:121], v[34:35], v[82:83] op_sel_hi:[0,1]
	ds_read_b128 v[62:65], v94 offset:20016
	v_pk_fma_f32 v[106:107], v[118:119], v[6:7], v[106:107]
	v_pk_fma_f32 v[108:109], v[118:119], v[26:27], v[108:109]
	v_pk_mul_f32 v[122:123], v[34:35], v[84:85] op_sel_hi:[0,1]
	ds_read_b128 v[58:61], v94 offset:20032
	v_pk_fma_f32 v[106:107], v[120:121], v[8:9], v[106:107]
	v_pk_fma_f32 v[108:109], v[120:121], v[28:29], v[108:109]
	v_pk_mul_f32 v[124:125], v[34:35], v[86:87] op_sel_hi:[0,1]
	ds_read_b128 v[54:57], v94 offset:20048
	v_pk_fma_f32 v[106:107], v[122:123], v[14:15], v[106:107]
	v_pk_fma_f32 v[108:109], v[122:123], v[22:23], v[108:109]
	v_pk_mul_f32 v[126:127], v[34:35], v[88:89] op_sel_hi:[0,1]
	ds_read_b128 v[50:53], v94 offset:20256
	v_pk_fma_f32 v[106:107], v[124:125], v[16:17], v[106:107]
	v_pk_fma_f32 v[108:109], v[124:125], v[24:25], v[108:109]
	v_pk_mul_f32 v[128:129], v[34:35], v[90:91] op_sel_hi:[0,1]
	ds_read_b128 v[46:49], v94 offset:20272
	v_pk_fma_f32 v[106:107], v[126:127], v[10:11], v[106:107]
	v_pk_fma_f32 v[108:109], v[126:127], v[18:19], v[108:109]
	ds_read_b128 v[42:45], v94 offset:20288
	v_pk_fma_f32 v[106:107], v[128:129], v[12:13], v[106:107]
	v_pk_fma_f32 v[108:109], v[128:129], v[20:21], v[108:109]
	ds_read_b128 v[38:41], v94 offset:20304
	v_add_f32_e32 v130, v106, v107
	v_add_f32_e32 v131, v108, v109
	ds_read_b32 v0, v95 offset:20512
	v_add_f32_dpp v130, v130, v130 quad_perm:[1,0,3,2] row_mask:0xf bank_mask:0xf bound_ctrl:1
	v_add_f32_dpp v131, v131, v131 quad_perm:[1,0,3,2] row_mask:0xf bank_mask:0xf bound_ctrl:1
	ds_read_b96 v[70:72], v1 offset:20768
	v_add_f32_dpp v130, v130, v130 quad_perm:[2,3,0,1] row_mask:0xf bank_mask:0xf bound_ctrl:1
	v_add_f32_dpp v131, v131, v131 quad_perm:[2,3,0,1] row_mask:0xf bank_mask:0xf bound_ctrl:1
	v_sub_f32_e32 v130, v73, v130
	v_mul_f32_e32 v130, v35, v130
	v_fma_f32 v131, v36, v130, v131
	v_cvt_pk_bf16_f32 v132, v131, v131
	v_pk_fma_f32 v[74:75], v[2:3], v[130:131], v[114:115] op_sel_hi:[1,0,1]
	v_pk_fma_f32 v[78:79], v[4:5], v[130:131], v[116:117] op_sel_hi:[1,0,1]
	global_store_short v152, v132, s[100:101]
	v_pk_fma_f32 v[80:81], v[6:7], v[130:131], v[118:119] op_sel_hi:[1,0,1]
	v_pk_fma_f32 v[82:83], v[8:9], v[130:131], v[120:121] op_sel_hi:[1,0,1]
	v_pk_fma_f32 v[84:85], v[14:15], v[130:131], v[122:123] op_sel_hi:[1,0,1]
	v_pk_fma_f32 v[86:87], v[16:17], v[130:131], v[124:125] op_sel_hi:[1,0,1]
	v_pk_fma_f32 v[88:89], v[10:11], v[130:131], v[126:127] op_sel_hi:[1,0,1]
	v_pk_fma_f32 v[90:91], v[12:13], v[130:131], v[128:129] op_sel_hi:[1,0,1]
	s_waitcnt lgkmcnt(0)
	v_pk_mul_f32 v[114:115], v[70:71], v[74:75] op_sel_hi:[0,1]
	v_pk_mul_f32 v[116:117], v[70:71], v[78:79] op_sel_hi:[0,1]
	v_pk_fma_f32 v[110:111], v[114:115], v[50:51], 0 op_sel_hi:[1,1,0]
	v_pk_fma_f32 v[112:113], v[114:115], v[66:67], 0 op_sel_hi:[1,1,0]
	v_pk_mul_f32 v[118:119], v[70:71], v[80:81] op_sel_hi:[0,1]
	ds_read_b128 v[30:33], v94 offset:20800
	v_pk_fma_f32 v[110:111], v[116:117], v[52:53], v[110:111]
	v_pk_fma_f32 v[112:113], v[116:117], v[68:69], v[112:113]
	v_pk_mul_f32 v[120:121], v[70:71], v[82:83] op_sel_hi:[0,1]
	ds_read_b128 v[26:29], v94 offset:20816
	v_pk_fma_f32 v[110:111], v[118:119], v[46:47], v[110:111]
	v_pk_fma_f32 v[112:113], v[118:119], v[62:63], v[112:113]
	v_pk_mul_f32 v[122:123], v[70:71], v[84:85] op_sel_hi:[0,1]
	ds_read_b128 v[22:25], v94 offset:20832
	v_pk_fma_f32 v[110:111], v[120:121], v[48:49], v[110:111]
	v_pk_fma_f32 v[112:113], v[120:121], v[64:65], v[112:113]
	v_pk_mul_f32 v[124:125], v[70:71], v[86:87] op_sel_hi:[0,1]
	ds_read_b128 v[18:21], v94 offset:20848
	v_pk_fma_f32 v[110:111], v[122:123], v[42:43], v[110:111]
	v_pk_fma_f32 v[112:113], v[122:123], v[58:59], v[112:113]
	v_pk_mul_f32 v[126:127], v[70:71], v[88:89] op_sel_hi:[0,1]
	ds_read_b128 v[2:5], v94 offset:21056
	v_pk_fma_f32 v[110:111], v[124:125], v[44:45], v[110:111]
	v_pk_fma_f32 v[112:113], v[124:125], v[60:61], v[112:113]
	v_pk_mul_f32 v[128:129], v[70:71], v[90:91] op_sel_hi:[0,1]
	ds_read_b128 v[6:9], v94 offset:21072
	v_pk_fma_f32 v[110:111], v[126:127], v[38:39], v[110:111]
	v_pk_fma_f32 v[112:113], v[126:127], v[54:55], v[112:113]
	ds_read_b128 v[14:17], v94 offset:21088
	v_pk_fma_f32 v[110:111], v[128:129], v[40:41], v[110:111]
	v_pk_fma_f32 v[112:113], v[128:129], v[56:57], v[112:113]
	ds_read_b128 v[10:13], v94 offset:21104
	v_add_f32_e32 v134, v110, v111
	v_add_f32_e32 v135, v112, v113
	ds_read_b32 v73, v95 offset:21312
	v_add_f32_dpp v134, v134, v134 quad_perm:[1,0,3,2] row_mask:0xf bank_mask:0xf bound_ctrl:1
	v_add_f32_dpp v135, v135, v135 quad_perm:[1,0,3,2] row_mask:0xf bank_mask:0xf bound_ctrl:1
	ds_read_b96 v[34:36], v1 offset:21568
	v_add_f32_dpp v134, v134, v134 quad_perm:[2,3,0,1] row_mask:0xf bank_mask:0xf bound_ctrl:1
	v_add_f32_dpp v135, v135, v135 quad_perm:[2,3,0,1] row_mask:0xf bank_mask:0xf bound_ctrl:1
	v_sub_f32_e32 v134, v0, v134
	v_mul_f32_e32 v134, v71, v134
	v_fma_f32 v135, v72, v134, v135
	v_cvt_pk_bf16_f32 v133, v135, v135
	v_pk_fma_f32 v[74:75], v[50:51], v[134:135], v[114:115] op_sel_hi:[1,0,1]
	v_pk_fma_f32 v[78:79], v[52:53], v[134:135], v[116:117] op_sel_hi:[1,0,1]
	global_store_short v153, v133, s[100:101]
	v_pk_fma_f32 v[80:81], v[46:47], v[134:135], v[118:119] op_sel_hi:[1,0,1]
	v_pk_fma_f32 v[82:83], v[48:49], v[134:135], v[120:121] op_sel_hi:[1,0,1]
	v_pk_fma_f32 v[84:85], v[42:43], v[134:135], v[122:123] op_sel_hi:[1,0,1]
	v_pk_fma_f32 v[86:87], v[44:45], v[134:135], v[124:125] op_sel_hi:[1,0,1]
	v_pk_fma_f32 v[88:89], v[38:39], v[134:135], v[126:127] op_sel_hi:[1,0,1]
	v_pk_fma_f32 v[90:91], v[40:41], v[134:135], v[128:129] op_sel_hi:[1,0,1]
	s_waitcnt lgkmcnt(0)
	v_pk_mul_f32 v[114:115], v[34:35], v[74:75] op_sel_hi:[0,1]
	v_pk_mul_f32 v[116:117], v[34:35], v[78:79] op_sel_hi:[0,1]
	v_pk_fma_f32 v[106:107], v[114:115], v[2:3], 0 op_sel_hi:[1,1,0]
	v_pk_fma_f32 v[108:109], v[114:115], v[30:31], 0 op_sel_hi:[1,1,0]
	v_pk_mul_f32 v[118:119], v[34:35], v[80:81] op_sel_hi:[0,1]
	ds_read_b128 v[66:69], v94 offset:21600
	v_pk_fma_f32 v[106:107], v[116:117], v[4:5], v[106:107]
	v_pk_fma_f32 v[108:109], v[116:117], v[32:33], v[108:109]
	v_pk_mul_f32 v[120:121], v[34:35], v[82:83] op_sel_hi:[0,1]
	ds_read_b128 v[62:65], v94 offset:21616
	v_pk_fma_f32 v[106:107], v[118:119], v[6:7], v[106:107]
	v_pk_fma_f32 v[108:109], v[118:119], v[26:27], v[108:109]
	v_pk_mul_f32 v[122:123], v[34:35], v[84:85] op_sel_hi:[0,1]
	ds_read_b128 v[58:61], v94 offset:21632
	v_pk_fma_f32 v[106:107], v[120:121], v[8:9], v[106:107]
	v_pk_fma_f32 v[108:109], v[120:121], v[28:29], v[108:109]
	v_pk_mul_f32 v[124:125], v[34:35], v[86:87] op_sel_hi:[0,1]
	ds_read_b128 v[54:57], v94 offset:21648
	v_pk_fma_f32 v[106:107], v[122:123], v[14:15], v[106:107]
	v_pk_fma_f32 v[108:109], v[122:123], v[22:23], v[108:109]
	v_pk_mul_f32 v[126:127], v[34:35], v[88:89] op_sel_hi:[0,1]
	ds_read_b128 v[50:53], v94 offset:21856
	v_pk_fma_f32 v[106:107], v[124:125], v[16:17], v[106:107]
	v_pk_fma_f32 v[108:109], v[124:125], v[24:25], v[108:109]
	v_pk_mul_f32 v[128:129], v[34:35], v[90:91] op_sel_hi:[0,1]
	ds_read_b128 v[46:49], v94 offset:21872
	v_pk_fma_f32 v[106:107], v[126:127], v[10:11], v[106:107]
	v_pk_fma_f32 v[108:109], v[126:127], v[18:19], v[108:109]
	ds_read_b128 v[42:45], v94 offset:21888
	v_pk_fma_f32 v[106:107], v[128:129], v[12:13], v[106:107]
	v_pk_fma_f32 v[108:109], v[128:129], v[20:21], v[108:109]
	ds_read_b128 v[38:41], v94 offset:21904
	v_add_f32_e32 v130, v106, v107
	v_add_f32_e32 v131, v108, v109
	ds_read_b32 v0, v95 offset:22112
	v_add_f32_dpp v130, v130, v130 quad_perm:[1,0,3,2] row_mask:0xf bank_mask:0xf bound_ctrl:1
	v_add_f32_dpp v131, v131, v131 quad_perm:[1,0,3,2] row_mask:0xf bank_mask:0xf bound_ctrl:1
	ds_read_b96 v[70:72], v1 offset:22368
	v_add_f32_dpp v130, v130, v130 quad_perm:[2,3,0,1] row_mask:0xf bank_mask:0xf bound_ctrl:1
	v_add_f32_dpp v131, v131, v131 quad_perm:[2,3,0,1] row_mask:0xf bank_mask:0xf bound_ctrl:1
	v_sub_f32_e32 v130, v73, v130
	v_mul_f32_e32 v130, v35, v130
	v_fma_f32 v131, v36, v130, v131
	v_cvt_pk_bf16_f32 v132, v131, v131
	v_pk_fma_f32 v[74:75], v[2:3], v[130:131], v[114:115] op_sel_hi:[1,0,1]
	v_pk_fma_f32 v[78:79], v[4:5], v[130:131], v[116:117] op_sel_hi:[1,0,1]
	global_store_short v154, v132, s[100:101]
	v_pk_fma_f32 v[80:81], v[6:7], v[130:131], v[118:119] op_sel_hi:[1,0,1]
	v_pk_fma_f32 v[82:83], v[8:9], v[130:131], v[120:121] op_sel_hi:[1,0,1]
	v_pk_fma_f32 v[84:85], v[14:15], v[130:131], v[122:123] op_sel_hi:[1,0,1]
	v_pk_fma_f32 v[86:87], v[16:17], v[130:131], v[124:125] op_sel_hi:[1,0,1]
	v_pk_fma_f32 v[88:89], v[10:11], v[130:131], v[126:127] op_sel_hi:[1,0,1]
	v_pk_fma_f32 v[90:91], v[12:13], v[130:131], v[128:129] op_sel_hi:[1,0,1]
	s_waitcnt lgkmcnt(0)
	v_pk_mul_f32 v[114:115], v[70:71], v[74:75] op_sel_hi:[0,1]
	v_pk_mul_f32 v[116:117], v[70:71], v[78:79] op_sel_hi:[0,1]
	v_pk_fma_f32 v[110:111], v[114:115], v[50:51], 0 op_sel_hi:[1,1,0]
	v_pk_fma_f32 v[112:113], v[114:115], v[66:67], 0 op_sel_hi:[1,1,0]
	v_pk_mul_f32 v[118:119], v[70:71], v[80:81] op_sel_hi:[0,1]
	ds_read_b128 v[30:33], v94 offset:22400
	v_pk_fma_f32 v[110:111], v[116:117], v[52:53], v[110:111]
	v_pk_fma_f32 v[112:113], v[116:117], v[68:69], v[112:113]
	v_pk_mul_f32 v[120:121], v[70:71], v[82:83] op_sel_hi:[0,1]
	ds_read_b128 v[26:29], v94 offset:22416
	v_pk_fma_f32 v[110:111], v[118:119], v[46:47], v[110:111]
	v_pk_fma_f32 v[112:113], v[118:119], v[62:63], v[112:113]
	v_pk_mul_f32 v[122:123], v[70:71], v[84:85] op_sel_hi:[0,1]
	ds_read_b128 v[22:25], v94 offset:22432
	v_pk_fma_f32 v[110:111], v[120:121], v[48:49], v[110:111]
	v_pk_fma_f32 v[112:113], v[120:121], v[64:65], v[112:113]
	v_pk_mul_f32 v[124:125], v[70:71], v[86:87] op_sel_hi:[0,1]
	ds_read_b128 v[18:21], v94 offset:22448
	v_pk_fma_f32 v[110:111], v[122:123], v[42:43], v[110:111]
	v_pk_fma_f32 v[112:113], v[122:123], v[58:59], v[112:113]
	v_pk_mul_f32 v[126:127], v[70:71], v[88:89] op_sel_hi:[0,1]
	ds_read_b128 v[2:5], v94 offset:22656
	v_pk_fma_f32 v[110:111], v[124:125], v[44:45], v[110:111]
	v_pk_fma_f32 v[112:113], v[124:125], v[60:61], v[112:113]
	v_pk_mul_f32 v[128:129], v[70:71], v[90:91] op_sel_hi:[0,1]
	ds_read_b128 v[6:9], v94 offset:22672
	v_pk_fma_f32 v[110:111], v[126:127], v[38:39], v[110:111]
	v_pk_fma_f32 v[112:113], v[126:127], v[54:55], v[112:113]
	ds_read_b128 v[14:17], v94 offset:22688
	v_pk_fma_f32 v[110:111], v[128:129], v[40:41], v[110:111]
	v_pk_fma_f32 v[112:113], v[128:129], v[56:57], v[112:113]
	ds_read_b128 v[10:13], v94 offset:22704
	v_add_f32_e32 v134, v110, v111
	v_add_f32_e32 v135, v112, v113
	ds_read_b32 v73, v95 offset:22912
	v_add_f32_dpp v134, v134, v134 quad_perm:[1,0,3,2] row_mask:0xf bank_mask:0xf bound_ctrl:1
	v_add_f32_dpp v135, v135, v135 quad_perm:[1,0,3,2] row_mask:0xf bank_mask:0xf bound_ctrl:1
	ds_read_b96 v[34:36], v1 offset:23168
	v_add_f32_dpp v134, v134, v134 quad_perm:[2,3,0,1] row_mask:0xf bank_mask:0xf bound_ctrl:1
	v_add_f32_dpp v135, v135, v135 quad_perm:[2,3,0,1] row_mask:0xf bank_mask:0xf bound_ctrl:1
	v_sub_f32_e32 v134, v0, v134
	v_mul_f32_e32 v134, v71, v134
	v_fma_f32 v135, v72, v134, v135
	v_cvt_pk_bf16_f32 v133, v135, v135
	v_pk_fma_f32 v[74:75], v[50:51], v[134:135], v[114:115] op_sel_hi:[1,0,1]
	v_pk_fma_f32 v[78:79], v[52:53], v[134:135], v[116:117] op_sel_hi:[1,0,1]
	global_store_short v155, v133, s[100:101]
	v_pk_fma_f32 v[80:81], v[46:47], v[134:135], v[118:119] op_sel_hi:[1,0,1]
	v_pk_fma_f32 v[82:83], v[48:49], v[134:135], v[120:121] op_sel_hi:[1,0,1]
	v_pk_fma_f32 v[84:85], v[42:43], v[134:135], v[122:123] op_sel_hi:[1,0,1]
	v_pk_fma_f32 v[86:87], v[44:45], v[134:135], v[124:125] op_sel_hi:[1,0,1]
	v_pk_fma_f32 v[88:89], v[38:39], v[134:135], v[126:127] op_sel_hi:[1,0,1]
	v_pk_fma_f32 v[90:91], v[40:41], v[134:135], v[128:129] op_sel_hi:[1,0,1]
	s_waitcnt lgkmcnt(0)
	v_pk_mul_f32 v[114:115], v[34:35], v[74:75] op_sel_hi:[0,1]
	v_pk_mul_f32 v[116:117], v[34:35], v[78:79] op_sel_hi:[0,1]
	v_pk_fma_f32 v[106:107], v[114:115], v[2:3], 0 op_sel_hi:[1,1,0]
	v_pk_fma_f32 v[108:109], v[114:115], v[30:31], 0 op_sel_hi:[1,1,0]
	v_pk_mul_f32 v[118:119], v[34:35], v[80:81] op_sel_hi:[0,1]
	ds_read_b128 v[66:69], v94 offset:23200
	v_pk_fma_f32 v[106:107], v[116:117], v[4:5], v[106:107]
	v_pk_fma_f32 v[108:109], v[116:117], v[32:33], v[108:109]
	v_pk_mul_f32 v[120:121], v[34:35], v[82:83] op_sel_hi:[0,1]
	ds_read_b128 v[62:65], v94 offset:23216
	v_pk_fma_f32 v[106:107], v[118:119], v[6:7], v[106:107]
	v_pk_fma_f32 v[108:109], v[118:119], v[26:27], v[108:109]
	v_pk_mul_f32 v[122:123], v[34:35], v[84:85] op_sel_hi:[0,1]
	ds_read_b128 v[58:61], v94 offset:23232
	v_pk_fma_f32 v[106:107], v[120:121], v[8:9], v[106:107]
	v_pk_fma_f32 v[108:109], v[120:121], v[28:29], v[108:109]
	v_pk_mul_f32 v[124:125], v[34:35], v[86:87] op_sel_hi:[0,1]
	ds_read_b128 v[54:57], v94 offset:23248
	v_pk_fma_f32 v[106:107], v[122:123], v[14:15], v[106:107]
	v_pk_fma_f32 v[108:109], v[122:123], v[22:23], v[108:109]
	v_pk_mul_f32 v[126:127], v[34:35], v[88:89] op_sel_hi:[0,1]
	ds_read_b128 v[50:53], v94 offset:23456
	v_pk_fma_f32 v[106:107], v[124:125], v[16:17], v[106:107]
	v_pk_fma_f32 v[108:109], v[124:125], v[24:25], v[108:109]
	v_pk_mul_f32 v[128:129], v[34:35], v[90:91] op_sel_hi:[0,1]
	ds_read_b128 v[46:49], v94 offset:23472
	v_pk_fma_f32 v[106:107], v[126:127], v[10:11], v[106:107]
	v_pk_fma_f32 v[108:109], v[126:127], v[18:19], v[108:109]
	ds_read_b128 v[42:45], v94 offset:23488
	v_pk_fma_f32 v[106:107], v[128:129], v[12:13], v[106:107]
	v_pk_fma_f32 v[108:109], v[128:129], v[20:21], v[108:109]
	ds_read_b128 v[38:41], v94 offset:23504
	v_add_f32_e32 v130, v106, v107
	v_add_f32_e32 v131, v108, v109
	ds_read_b32 v0, v95 offset:23712
	v_add_f32_dpp v130, v130, v130 quad_perm:[1,0,3,2] row_mask:0xf bank_mask:0xf bound_ctrl:1
	v_add_f32_dpp v131, v131, v131 quad_perm:[1,0,3,2] row_mask:0xf bank_mask:0xf bound_ctrl:1
	ds_read_b96 v[70:72], v1 offset:23968
	v_add_f32_dpp v130, v130, v130 quad_perm:[2,3,0,1] row_mask:0xf bank_mask:0xf bound_ctrl:1
	v_add_f32_dpp v131, v131, v131 quad_perm:[2,3,0,1] row_mask:0xf bank_mask:0xf bound_ctrl:1
	v_sub_f32_e32 v130, v73, v130
	v_mul_f32_e32 v130, v35, v130
	v_fma_f32 v131, v36, v130, v131
	v_cvt_pk_bf16_f32 v132, v131, v131
	v_pk_fma_f32 v[74:75], v[2:3], v[130:131], v[114:115] op_sel_hi:[1,0,1]
	v_pk_fma_f32 v[78:79], v[4:5], v[130:131], v[116:117] op_sel_hi:[1,0,1]
	global_store_short v156, v132, s[100:101]
	v_pk_fma_f32 v[80:81], v[6:7], v[130:131], v[118:119] op_sel_hi:[1,0,1]
	v_pk_fma_f32 v[82:83], v[8:9], v[130:131], v[120:121] op_sel_hi:[1,0,1]
	v_pk_fma_f32 v[84:85], v[14:15], v[130:131], v[122:123] op_sel_hi:[1,0,1]
	v_pk_fma_f32 v[86:87], v[16:17], v[130:131], v[124:125] op_sel_hi:[1,0,1]
	v_pk_fma_f32 v[88:89], v[10:11], v[130:131], v[126:127] op_sel_hi:[1,0,1]
	v_pk_fma_f32 v[90:91], v[12:13], v[130:131], v[128:129] op_sel_hi:[1,0,1]
	s_waitcnt lgkmcnt(0)
	v_pk_mul_f32 v[114:115], v[70:71], v[74:75] op_sel_hi:[0,1]
	v_pk_mul_f32 v[116:117], v[70:71], v[78:79] op_sel_hi:[0,1]
	v_pk_fma_f32 v[110:111], v[114:115], v[50:51], 0 op_sel_hi:[1,1,0]
	v_pk_fma_f32 v[112:113], v[114:115], v[66:67], 0 op_sel_hi:[1,1,0]
	v_pk_mul_f32 v[118:119], v[70:71], v[80:81] op_sel_hi:[0,1]
	ds_read_b128 v[30:33], v94 offset:24000
	v_pk_fma_f32 v[110:111], v[116:117], v[52:53], v[110:111]
	v_pk_fma_f32 v[112:113], v[116:117], v[68:69], v[112:113]
	v_pk_mul_f32 v[120:121], v[70:71], v[82:83] op_sel_hi:[0,1]
	ds_read_b128 v[26:29], v94 offset:24016
	v_pk_fma_f32 v[110:111], v[118:119], v[46:47], v[110:111]
	v_pk_fma_f32 v[112:113], v[118:119], v[62:63], v[112:113]
	v_pk_mul_f32 v[122:123], v[70:71], v[84:85] op_sel_hi:[0,1]
	ds_read_b128 v[22:25], v94 offset:24032
	v_pk_fma_f32 v[110:111], v[120:121], v[48:49], v[110:111]
	v_pk_fma_f32 v[112:113], v[120:121], v[64:65], v[112:113]
	v_pk_mul_f32 v[124:125], v[70:71], v[86:87] op_sel_hi:[0,1]
	ds_read_b128 v[18:21], v94 offset:24048
	v_pk_fma_f32 v[110:111], v[122:123], v[42:43], v[110:111]
	v_pk_fma_f32 v[112:113], v[122:123], v[58:59], v[112:113]
	v_pk_mul_f32 v[126:127], v[70:71], v[88:89] op_sel_hi:[0,1]
	ds_read_b128 v[2:5], v94 offset:24256
	v_pk_fma_f32 v[110:111], v[124:125], v[44:45], v[110:111]
	v_pk_fma_f32 v[112:113], v[124:125], v[60:61], v[112:113]
	v_pk_mul_f32 v[128:129], v[70:71], v[90:91] op_sel_hi:[0,1]
	ds_read_b128 v[6:9], v94 offset:24272
	v_pk_fma_f32 v[110:111], v[126:127], v[38:39], v[110:111]
	v_pk_fma_f32 v[112:113], v[126:127], v[54:55], v[112:113]
	ds_read_b128 v[14:17], v94 offset:24288
	v_pk_fma_f32 v[110:111], v[128:129], v[40:41], v[110:111]
	v_pk_fma_f32 v[112:113], v[128:129], v[56:57], v[112:113]
	ds_read_b128 v[10:13], v94 offset:24304
	v_add_f32_e32 v134, v110, v111
	v_add_f32_e32 v135, v112, v113
	ds_read_b32 v73, v95 offset:24512
	v_add_f32_dpp v134, v134, v134 quad_perm:[1,0,3,2] row_mask:0xf bank_mask:0xf bound_ctrl:1
	v_add_f32_dpp v135, v135, v135 quad_perm:[1,0,3,2] row_mask:0xf bank_mask:0xf bound_ctrl:1
	ds_read_b96 v[34:36], v1 offset:24768
	v_add_f32_dpp v134, v134, v134 quad_perm:[2,3,0,1] row_mask:0xf bank_mask:0xf bound_ctrl:1
	v_add_f32_dpp v135, v135, v135 quad_perm:[2,3,0,1] row_mask:0xf bank_mask:0xf bound_ctrl:1
	v_sub_f32_e32 v134, v0, v134
	v_mul_f32_e32 v134, v71, v134
	v_fma_f32 v135, v72, v134, v135
	v_cvt_pk_bf16_f32 v133, v135, v135
	v_pk_fma_f32 v[74:75], v[50:51], v[134:135], v[114:115] op_sel_hi:[1,0,1]
	v_pk_fma_f32 v[78:79], v[52:53], v[134:135], v[116:117] op_sel_hi:[1,0,1]
	global_store_short v157, v133, s[100:101]
	v_pk_fma_f32 v[80:81], v[46:47], v[134:135], v[118:119] op_sel_hi:[1,0,1]
	v_pk_fma_f32 v[82:83], v[48:49], v[134:135], v[120:121] op_sel_hi:[1,0,1]
	v_pk_fma_f32 v[84:85], v[42:43], v[134:135], v[122:123] op_sel_hi:[1,0,1]
	v_pk_fma_f32 v[86:87], v[44:45], v[134:135], v[124:125] op_sel_hi:[1,0,1]
	v_pk_fma_f32 v[88:89], v[38:39], v[134:135], v[126:127] op_sel_hi:[1,0,1]
	v_pk_fma_f32 v[90:91], v[40:41], v[134:135], v[128:129] op_sel_hi:[1,0,1]
	s_waitcnt lgkmcnt(0)
	v_pk_mul_f32 v[114:115], v[34:35], v[74:75] op_sel_hi:[0,1]
	v_pk_mul_f32 v[116:117], v[34:35], v[78:79] op_sel_hi:[0,1]
	v_pk_fma_f32 v[106:107], v[114:115], v[2:3], 0 op_sel_hi:[1,1,0]
	v_pk_fma_f32 v[108:109], v[114:115], v[30:31], 0 op_sel_hi:[1,1,0]
	v_pk_mul_f32 v[118:119], v[34:35], v[80:81] op_sel_hi:[0,1]
	ds_read_b128 v[66:69], v94 offset:24800
	v_pk_fma_f32 v[106:107], v[116:117], v[4:5], v[106:107]
	v_pk_fma_f32 v[108:109], v[116:117], v[32:33], v[108:109]
	v_pk_mul_f32 v[120:121], v[34:35], v[82:83] op_sel_hi:[0,1]
	ds_read_b128 v[62:65], v94 offset:24816
	v_pk_fma_f32 v[106:107], v[118:119], v[6:7], v[106:107]
	v_pk_fma_f32 v[108:109], v[118:119], v[26:27], v[108:109]
	v_pk_mul_f32 v[122:123], v[34:35], v[84:85] op_sel_hi:[0,1]
	ds_read_b128 v[58:61], v94 offset:24832
	v_pk_fma_f32 v[106:107], v[120:121], v[8:9], v[106:107]
	v_pk_fma_f32 v[108:109], v[120:121], v[28:29], v[108:109]
	v_pk_mul_f32 v[124:125], v[34:35], v[86:87] op_sel_hi:[0,1]
	ds_read_b128 v[54:57], v94 offset:24848
	v_pk_fma_f32 v[106:107], v[122:123], v[14:15], v[106:107]
	v_pk_fma_f32 v[108:109], v[122:123], v[22:23], v[108:109]
	v_pk_mul_f32 v[126:127], v[34:35], v[88:89] op_sel_hi:[0,1]
	ds_read_b128 v[50:53], v94 offset:25056
	v_pk_fma_f32 v[106:107], v[124:125], v[16:17], v[106:107]
	v_pk_fma_f32 v[108:109], v[124:125], v[24:25], v[108:109]
	v_pk_mul_f32 v[128:129], v[34:35], v[90:91] op_sel_hi:[0,1]
	ds_read_b128 v[46:49], v94 offset:25072
	v_pk_fma_f32 v[106:107], v[126:127], v[10:11], v[106:107]
	v_pk_fma_f32 v[108:109], v[126:127], v[18:19], v[108:109]
	ds_read_b128 v[42:45], v94 offset:25088
	v_pk_fma_f32 v[106:107], v[128:129], v[12:13], v[106:107]
	v_pk_fma_f32 v[108:109], v[128:129], v[20:21], v[108:109]
	ds_read_b128 v[38:41], v94 offset:25104
	v_add_f32_e32 v130, v106, v107
	v_add_f32_e32 v131, v108, v109
	ds_read_b32 v0, v95 offset:25312
	v_add_f32_dpp v130, v130, v130 quad_perm:[1,0,3,2] row_mask:0xf bank_mask:0xf bound_ctrl:1
	v_add_f32_dpp v131, v131, v131 quad_perm:[1,0,3,2] row_mask:0xf bank_mask:0xf bound_ctrl:1
	ds_read_b96 v[70:72], v1 offset:25568
	v_add_f32_dpp v130, v130, v130 quad_perm:[2,3,0,1] row_mask:0xf bank_mask:0xf bound_ctrl:1
	v_add_f32_dpp v131, v131, v131 quad_perm:[2,3,0,1] row_mask:0xf bank_mask:0xf bound_ctrl:1
	v_sub_f32_e32 v130, v73, v130
	v_mul_f32_e32 v130, v35, v130
	v_fma_f32 v131, v36, v130, v131
	v_cvt_pk_bf16_f32 v132, v131, v131
	v_pk_fma_f32 v[74:75], v[2:3], v[130:131], v[114:115] op_sel_hi:[1,0,1]
	v_pk_fma_f32 v[78:79], v[4:5], v[130:131], v[116:117] op_sel_hi:[1,0,1]
	global_store_short v158, v132, s[100:101]
	v_pk_fma_f32 v[80:81], v[6:7], v[130:131], v[118:119] op_sel_hi:[1,0,1]
	v_pk_fma_f32 v[82:83], v[8:9], v[130:131], v[120:121] op_sel_hi:[1,0,1]
	v_pk_fma_f32 v[84:85], v[14:15], v[130:131], v[122:123] op_sel_hi:[1,0,1]
	v_pk_fma_f32 v[86:87], v[16:17], v[130:131], v[124:125] op_sel_hi:[1,0,1]
	v_pk_fma_f32 v[88:89], v[10:11], v[130:131], v[126:127] op_sel_hi:[1,0,1]
	v_pk_fma_f32 v[90:91], v[12:13], v[130:131], v[128:129] op_sel_hi:[1,0,1]
	s_waitcnt lgkmcnt(0)
	v_pk_mul_f32 v[114:115], v[70:71], v[74:75] op_sel_hi:[0,1]
	v_pk_mul_f32 v[116:117], v[70:71], v[78:79] op_sel_hi:[0,1]
	v_pk_fma_f32 v[110:111], v[114:115], v[50:51], 0 op_sel_hi:[1,1,0]
	v_pk_fma_f32 v[112:113], v[114:115], v[66:67], 0 op_sel_hi:[1,1,0]
	v_pk_mul_f32 v[118:119], v[70:71], v[80:81] op_sel_hi:[0,1]
	v_pk_fma_f32 v[110:111], v[116:117], v[52:53], v[110:111]
	v_pk_fma_f32 v[112:113], v[116:117], v[68:69], v[112:113]
	v_pk_mul_f32 v[120:121], v[70:71], v[82:83] op_sel_hi:[0,1]
	v_pk_fma_f32 v[110:111], v[118:119], v[46:47], v[110:111]
	v_pk_fma_f32 v[112:113], v[118:119], v[62:63], v[112:113]
	v_pk_mul_f32 v[122:123], v[70:71], v[84:85] op_sel_hi:[0,1]
	v_pk_fma_f32 v[110:111], v[120:121], v[48:49], v[110:111]
	v_pk_fma_f32 v[112:113], v[120:121], v[64:65], v[112:113]
	v_pk_mul_f32 v[124:125], v[70:71], v[86:87] op_sel_hi:[0,1]
	v_pk_fma_f32 v[110:111], v[122:123], v[42:43], v[110:111]
	v_pk_fma_f32 v[112:113], v[122:123], v[58:59], v[112:113]
	v_pk_mul_f32 v[126:127], v[70:71], v[88:89] op_sel_hi:[0,1]
	v_pk_fma_f32 v[110:111], v[124:125], v[44:45], v[110:111]
	v_pk_fma_f32 v[112:113], v[124:125], v[60:61], v[112:113]
	v_pk_mul_f32 v[128:129], v[70:71], v[90:91] op_sel_hi:[0,1]
	v_pk_fma_f32 v[110:111], v[126:127], v[38:39], v[110:111]
	v_pk_fma_f32 v[112:113], v[126:127], v[54:55], v[112:113]
	v_pk_fma_f32 v[110:111], v[128:129], v[40:41], v[110:111]
	v_pk_fma_f32 v[112:113], v[128:129], v[56:57], v[112:113]
	v_add_f32_e32 v134, v110, v111
	v_add_f32_e32 v135, v112, v113
	s_nop 0
	v_add_f32_dpp v134, v134, v134 quad_perm:[1,0,3,2] row_mask:0xf bank_mask:0xf bound_ctrl:1
	v_add_f32_dpp v135, v135, v135 quad_perm:[1,0,3,2] row_mask:0xf bank_mask:0xf bound_ctrl:1
	s_nop 0
	v_add_f32_dpp v134, v134, v134 quad_perm:[2,3,0,1] row_mask:0xf bank_mask:0xf bound_ctrl:1
	v_add_f32_dpp v135, v135, v135 quad_perm:[2,3,0,1] row_mask:0xf bank_mask:0xf bound_ctrl:1
	v_sub_f32_e32 v134, v0, v134
	v_mul_f32_e32 v134, v71, v134
	v_fma_f32 v135, v72, v134, v135
	v_cvt_pk_bf16_f32 v133, v135, v135
	v_pk_fma_f32 v[74:75], v[50:51], v[134:135], v[114:115] op_sel_hi:[1,0,1]
	v_pk_fma_f32 v[78:79], v[52:53], v[134:135], v[116:117] op_sel_hi:[1,0,1]
	global_store_short v159, v133, s[100:101]
	v_pk_fma_f32 v[80:81], v[46:47], v[134:135], v[118:119] op_sel_hi:[1,0,1]
	v_pk_fma_f32 v[82:83], v[48:49], v[134:135], v[120:121] op_sel_hi:[1,0,1]
	v_pk_fma_f32 v[84:85], v[42:43], v[134:135], v[122:123] op_sel_hi:[1,0,1]
	v_pk_fma_f32 v[86:87], v[44:45], v[134:135], v[124:125] op_sel_hi:[1,0,1]
	v_pk_fma_f32 v[88:89], v[38:39], v[134:135], v[126:127] op_sel_hi:[1,0,1]
	v_pk_fma_f32 v[90:91], v[40:41], v[134:135], v[128:129] op_sel_hi:[1,0,1]
	s_branch .LBB0_899
